# GEMM mainloops: vmcnt(8) and lgkmcnt(0) before each sub-phase barrier merged into one s_waitcnt (16 sites)
# speedup vs baseline: 1.0069x; 1.0016x over previous
; #define PG8_STAGE(bufoff, gbase, voff) do { _Pragma("unroll") for (int _i = 0; _i < 2; ++_i) \
;         __builtin_amdgcn_global_load_lds((const unsigned*)((const char*)(gbase) + (voff)[_i]), (PG8_LAS unsigned*)(lds + (bufoff) + ldsw + _i * 8192), 16, 0, 0); } while (0)
; #define PG8_LDA(dst, b, h) do { _Pragma("unroll") for (int m = 0; m < 4; ++m) _Pragma("unroll") for (int k = 0; k < 2; ++k) dst[m][k] = *(const PG8_LAS bf16x8*)(lds + PG8_SA(b, h) + aoff + m * 2048 + k * 1024); } while (0)
; #define PG8_LDB(dst, b, h) do { _Pragma("unroll") for (int n = 0; n < 2; ++n) _Pragma("unroll") for (int k = 0; k < 2; ++k) dst[n][k] = *(const PG8_LAS bf16x8*)(lds + PG8_SB(b, h) + boff + n * 2048 + k * 1024); } while (0)
; #define PG8_MMA(ai, bj, At, Bt) do { __builtin_amdgcn_s_setprio(1); _Pragma("unroll") for (int m = 0; m < 4; ++m) _Pragma("unroll") for (int n = 0; n < 2; ++n) _Pragma("unroll") for (int k = 0; k < 2; ++k) \
;         acc[ai][bj][m][n] = __builtin_amdgcn_mfma_f32_16x16x32_bf16(Bt[n][k], At[m][k], acc[ai][bj][m][n], 0, 0, 0); __builtin_amdgcn_s_setprio(0); } while (0)
; #define PG8_WAIT_V(n) asm volatile("s_waitcnt vmcnt(" #n ")" ::: "memory")
; #define PG8_WAIT_L(n) asm volatile("s_waitcnt lgkmcnt(" #n ")" ::: "memory")
; #define PG8_BAR __builtin_amdgcn_s_barrier()
; #define PG8_SCHED __builtin_amdgcn_sched_barrier(0)
; template <class Epi, class Sched, bool ALIGN_EPI = false, bool SP2 = false>
; __device__ __forceinline__ void gemm_phase(PG8_LAS unsigned char* lds, const Gemm g, const Sched& S, const Epi& E) {
;     ...
;             PG8_LDB(B0, 0, 0); PG8_LDB(B1, 0, 1); PG8_SCHED; PG8_LDA(At, 0, 0); PG8_STAGE(PG8_SA(1, 1), a1 + hstep, voffA);
;             PG8_WAIT_V(8); PG8_WAIT_L(0); PG8_BAR; PG8_MMA(0, 0, At, B0); PG8_MMA(0, 1, At, B1); PG8_BAR; PG8_SCHED;
;             PG8_LDA(At, 0, 1); PG8_STAGE(PG8_SB(0, 0), b2, voffB); PG8_STAGE(PG8_SB(0, 1), b2 + hstep, voffB); PG8_STAGE(PG8_SA(0, 0), a2, voffA);
;             PG8_WAIT_V(8); PG8_WAIT_L(0); PG8_BAR; PG8_MMA(1, 0, At, B0); PG8_MMA(1, 1, At, B1); PG8_BAR; PG8_SCHED;
.LBB0_67:
	ds_read_b128 v[144:147], v155
	ds_read_b128 v[158:161], v155 offset:1024
	ds_read_b128 v[162:165], v155 offset:2048
	ds_read_b128 v[166:169], v155 offset:3072
	ds_read_b128 v[170:173], v156
	ds_read_b128 v[174:177], v156 offset:1024
	ds_read_b128 v[178:181], v156 offset:2048
	ds_read_b128 v[182:185], v156 offset:3072
	s_add_u32 s26, s24, 0xfffc0080
	s_addc_u32 s27, s25, -1
	s_cmp_eq_u32 s50, 12
	s_cselect_b32 s29, s15, s27
	s_cselect_b32 s28, s46, s26
	s_cselect_b32 s27, s13, s49
	s_cselect_b32 s26, s47, s48
	v_lshl_add_u64 v[218:219], s[24:25], 0, v[136:137]
	s_add_i32 m0, s23, 0xc000
	ds_read_b128 v[186:189], v157
	ds_read_b128 v[190:193], v157 offset:1024
	ds_read_b128 v[194:197], v157 offset:2048
	ds_read_b128 v[198:201], v157 offset:3072
	ds_read_b128 v[202:205], v157 offset:4096
	ds_read_b128 v[206:209], v157 offset:5120
	ds_read_b128 v[210:213], v157 offset:6144
	ds_read_b128 v[214:217], v157 offset:7168
	global_load_lds_dwordx4 v[218:219], off
	v_lshl_add_u64 v[218:219], s[24:25], 0, v[138:139]
	s_add_i32 m0, s23, 0xe000
	s_nop 0
	global_load_lds_dwordx4 v[218:219], off
	s_waitcnt vmcnt(8) lgkmcnt(0)
	s_barrier
	s_setprio 1
	v_mfma_f32_16x16x32_bf16 v[124:127], v[144:147], v[186:189], v[124:127]
	v_mfma_f32_16x16x32_bf16 v[120:123], v[162:165], v[186:189], v[120:123]
	v_mfma_f32_16x16x32_bf16 v[116:119], v[144:147], v[194:197], v[116:119]
	v_mfma_f32_16x16x32_bf16 v[112:115], v[162:165], v[194:197], v[112:115]
	v_mfma_f32_16x16x32_bf16 v[104:107], v[144:147], v[202:205], v[104:107]
	v_mfma_f32_16x16x32_bf16 v[96:99], v[162:165], v[202:205], v[96:99]
	v_mfma_f32_16x16x32_bf16 v[76:79], v[144:147], v[210:213], v[76:79]
	v_mfma_f32_16x16x32_bf16 v[72:75], v[162:165], v[210:213], v[72:75]
	v_mfma_f32_16x16x32_bf16 v[124:127], v[158:161], v[190:193], v[124:127]
	v_mfma_f32_16x16x32_bf16 v[120:123], v[166:169], v[190:193], v[120:123]
	v_mfma_f32_16x16x32_bf16 v[116:119], v[158:161], v[198:201], v[116:119]
	v_mfma_f32_16x16x32_bf16 v[112:115], v[166:169], v[198:201], v[112:115]
	v_mfma_f32_16x16x32_bf16 v[104:107], v[158:161], v[206:209], v[104:107]
	v_mfma_f32_16x16x32_bf16 v[96:99], v[166:169], v[206:209], v[96:99]
	v_mfma_f32_16x16x32_bf16 v[76:79], v[158:161], v[214:217], v[76:79]
	v_mfma_f32_16x16x32_bf16 v[72:75], v[166:169], v[214:217], v[72:75]
	s_setprio 0
	s_setprio 1
	v_mfma_f32_16x16x32_bf16 v[108:111], v[170:173], v[186:189], v[108:111]
	v_mfma_f32_16x16x32_bf16 v[100:103], v[178:181], v[186:189], v[100:103]
	v_mfma_f32_16x16x32_bf16 v[92:95], v[170:173], v[194:197], v[92:95]
	v_mfma_f32_16x16x32_bf16 v[88:91], v[178:181], v[194:197], v[88:91]
	v_mfma_f32_16x16x32_bf16 v[84:87], v[170:173], v[202:205], v[84:87]
	v_mfma_f32_16x16x32_bf16 v[80:83], v[178:181], v[202:205], v[80:83]
	v_mfma_f32_16x16x32_bf16 v[68:71], v[170:173], v[210:213], v[68:71]
	v_mfma_f32_16x16x32_bf16 v[64:67], v[178:181], v[210:213], v[64:67]
	v_mfma_f32_16x16x32_bf16 v[108:111], v[174:177], v[190:193], v[108:111]
	v_mfma_f32_16x16x32_bf16 v[100:103], v[182:185], v[190:193], v[100:103]
	v_mfma_f32_16x16x32_bf16 v[92:95], v[174:177], v[198:201], v[92:95]
	v_mfma_f32_16x16x32_bf16 v[88:91], v[182:185], v[198:201], v[88:91]
	v_mfma_f32_16x16x32_bf16 v[84:87], v[174:177], v[206:209], v[84:87]
	v_mfma_f32_16x16x32_bf16 v[80:83], v[182:185], v[206:209], v[80:83]
	v_mfma_f32_16x16x32_bf16 v[68:71], v[174:177], v[214:217], v[68:71]
	v_mfma_f32_16x16x32_bf16 v[64:67], v[182:185], v[214:217], v[64:67]
	s_setprio 0
	s_barrier
	s_add_i32 s51, s42, s30
	v_lshl_add_u64 v[218:219], s[26:27], 0, v[132:133]
	s_mov_b32 m0, s51
	ds_read_b128 v[186:189], v157 offset:16384
	ds_read_b128 v[190:193], v157 offset:17408
	ds_read_b128 v[194:197], v157 offset:18432
	ds_read_b128 v[198:201], v157 offset:19456
	ds_read_b128 v[202:205], v157 offset:20480
	ds_read_b128 v[206:209], v157 offset:21504
	ds_read_b128 v[210:213], v157 offset:22528
	ds_read_b128 v[214:217], v157 offset:23552
	global_load_lds_dwordx4 v[218:219], off
	s_add_i32 m0, s51, 0x2000
	s_add_u32 s52, s26, 0x40000
	v_lshl_add_u64 v[220:221], s[26:27], 0, v[128:129]
	s_addc_u32 s53, s27, 0
	s_add_i32 s51, s43, s30
	global_load_lds_dwordx4 v[220:221], off
	v_lshl_add_u64 v[222:223], s[52:53], 0, v[132:133]
	s_mov_b32 m0, s51
	v_lshl_add_u64 v[224:225], s[28:29], 0, v[130:131]
	global_load_lds_dwordx4 v[222:223], off
	v_lshl_add_u64 v[222:223], s[52:53], 0, v[128:129]
	s_add_i32 m0, s51, 0x2000
	s_nop 0
	global_load_lds_dwordx4 v[222:223], off
	v_lshl_add_u64 v[222:223], s[28:29], 0, v[134:135]
	s_mov_b32 m0, s23
	s_nop 0
	global_load_lds_dwordx4 v[222:223], off
	s_mov_b32 m0, s34
	s_nop 0
	global_load_lds_dwordx4 v[224:225], off
	s_waitcnt vmcnt(8) lgkmcnt(0)
	s_barrier
; #define PG8_STAGE(bufoff, gbase, voff) do { _Pragma("unroll") for (int _i = 0; _i < 2; ++_i) \
;         __builtin_amdgcn_global_load_lds((const unsigned*)((const char*)(gbase) + (voff)[_i]), (PG8_LAS unsigned*)(lds + (bufoff) + ldsw + _i * 8192), 16, 0, 0); } while (0)
; #define PG8_LDA(dst, b, h) do { _Pragma("unroll") for (int m = 0; m < 4; ++m) _Pragma("unroll") for (int k = 0; k < 2; ++k) dst[m][k] = *(const PG8_LAS bf16x8*)(lds + PG8_SA(b, h) + aoff + m * 2048 + k * 1024); } while (0)
; #define PG8_LDB(dst, b, h) do { _Pragma("unroll") for (int n = 0; n < 2; ++n) _Pragma("unroll") for (int k = 0; k < 2; ++k) dst[n][k] = *(const PG8_LAS bf16x8*)(lds + PG8_SB(b, h) + boff + n * 2048 + k * 1024); } while (0)
; #define PG8_MMA(ai, bj, At, Bt) do { __builtin_amdgcn_s_setprio(1); _Pragma("unroll") for (int m = 0; m < 4; ++m) _Pragma("unroll") for (int n = 0; n < 2; ++n) _Pragma("unroll") for (int k = 0; k < 2; ++k) \
;         acc[ai][bj][m][n] = __builtin_amdgcn_mfma_f32_16x16x32_bf16(Bt[n][k], At[m][k], acc[ai][bj][m][n], 0, 0, 0); __builtin_amdgcn_s_setprio(0); } while (0)
; #define PG8_WAIT_V(n) asm volatile("s_waitcnt vmcnt(" #n ")" ::: "memory")
; #define PG8_WAIT_L(n) asm volatile("s_waitcnt lgkmcnt(" #n ")" ::: "memory")
; #define PG8_BAR __builtin_amdgcn_s_barrier()
; #define PG8_SCHED __builtin_amdgcn_sched_barrier(0)
; template <class Epi, class Sched, bool ALIGN_EPI = false, bool SP2 = false>
; __device__ __forceinline__ void gemm_phase(PG8_LAS unsigned char* lds, const Gemm g, const Sched& S, const Epi& E) {
;     ...
;             PG8_WAIT_V(8); PG8_WAIT_L(0); PG8_BAR; PG8_MMA(1, 0, At, B0); PG8_MMA(1, 1, At, B1); PG8_BAR; PG8_SCHED;
;             PG8_LDB(B0, 1, 0); PG8_LDB(B1, 1, 1); PG8_SCHED; PG8_LDA(At, 1, 0); PG8_STAGE(PG8_SA(0, 1), a2 + hstep, voffA);
;             PG8_WAIT_V(8); PG8_WAIT_L(0); PG8_BAR; PG8_MMA(0, 0, At, B0); PG8_MMA(0, 1, At, B1); PG8_BAR; PG8_SCHED;
	s_setprio 1
	v_mfma_f32_16x16x32_bf16 v[60:63], v[144:147], v[186:189], v[60:63]
	v_mfma_f32_16x16x32_bf16 v[56:59], v[162:165], v[186:189], v[56:59]
	v_mfma_f32_16x16x32_bf16 v[48:51], v[144:147], v[194:197], v[48:51]
	v_mfma_f32_16x16x32_bf16 v[40:43], v[162:165], v[194:197], v[40:43]
	v_mfma_f32_16x16x32_bf16 v[32:35], v[144:147], v[202:205], v[32:35]
	v_mfma_f32_16x16x32_bf16 v[24:27], v[162:165], v[202:205], v[24:27]
	v_mfma_f32_16x16x32_bf16 v[16:19], v[144:147], v[210:213], v[16:19]
	v_mfma_f32_16x16x32_bf16 v[8:11], v[162:165], v[210:213], v[8:11]
	v_mfma_f32_16x16x32_bf16 v[60:63], v[158:161], v[190:193], v[60:63]
	v_mfma_f32_16x16x32_bf16 v[56:59], v[166:169], v[190:193], v[56:59]
	v_mfma_f32_16x16x32_bf16 v[48:51], v[158:161], v[198:201], v[48:51]
	v_mfma_f32_16x16x32_bf16 v[40:43], v[166:169], v[198:201], v[40:43]
	v_mfma_f32_16x16x32_bf16 v[32:35], v[158:161], v[206:209], v[32:35]
	v_mfma_f32_16x16x32_bf16 v[24:27], v[166:169], v[206:209], v[24:27]
	v_mfma_f32_16x16x32_bf16 v[16:19], v[158:161], v[214:217], v[16:19]
	v_mfma_f32_16x16x32_bf16 v[8:11], v[166:169], v[214:217], v[8:11]
	s_setprio 0
	s_setprio 1
	v_mfma_f32_16x16x32_bf16 v[52:55], v[170:173], v[186:189], v[52:55]
	v_mfma_f32_16x16x32_bf16 v[44:47], v[178:181], v[186:189], v[44:47]
	v_mfma_f32_16x16x32_bf16 v[36:39], v[170:173], v[194:197], v[36:39]
	v_mfma_f32_16x16x32_bf16 v[28:31], v[178:181], v[194:197], v[28:31]
	v_mfma_f32_16x16x32_bf16 v[20:23], v[170:173], v[202:205], v[20:23]
	v_mfma_f32_16x16x32_bf16 v[12:15], v[178:181], v[202:205], v[12:15]
	v_mfma_f32_16x16x32_bf16 v[4:7], v[170:173], v[210:213], v[4:7]
	v_mfma_f32_16x16x32_bf16 v[0:3], v[178:181], v[210:213], v[0:3]
	v_mfma_f32_16x16x32_bf16 v[52:55], v[174:177], v[190:193], v[52:55]
	v_mfma_f32_16x16x32_bf16 v[44:47], v[182:185], v[190:193], v[44:47]
	v_mfma_f32_16x16x32_bf16 v[36:39], v[174:177], v[198:201], v[36:39]
	v_mfma_f32_16x16x32_bf16 v[28:31], v[182:185], v[198:201], v[28:31]
	v_mfma_f32_16x16x32_bf16 v[20:23], v[174:177], v[206:209], v[20:23]
	v_mfma_f32_16x16x32_bf16 v[12:15], v[182:185], v[206:209], v[12:15]
	v_mfma_f32_16x16x32_bf16 v[4:7], v[174:177], v[214:217], v[4:7]
	v_mfma_f32_16x16x32_bf16 v[0:3], v[182:185], v[214:217], v[0:3]
	s_setprio 0
	s_barrier
	s_add_i32 s51, 0, 0x18000
	v_add_u32_e32 v148, s51, v151
	s_add_i32 s52, 0, 0x1c000
	ds_read_b128 v[144:147], v148
	ds_read_b128 v[158:161], v148 offset:1024
	ds_read_b128 v[162:165], v148 offset:2048
	ds_read_b128 v[166:169], v148 offset:3072
	v_add_u32_e32 v148, s52, v151
	ds_read_b128 v[170:173], v148
	ds_read_b128 v[174:177], v148 offset:1024
	ds_read_b128 v[178:181], v148 offset:2048
	ds_read_b128 v[182:185], v148 offset:3072
	s_add_u32 s28, s28, 0x40000
	s_addc_u32 s29, s29, 0
	s_mov_b32 m0, s35
	v_lshl_add_u64 v[226:227], s[28:29], 0, v[134:135]
	ds_read_b128 v[186:189], v157 offset:32768
	ds_read_b128 v[190:193], v157 offset:33792
	ds_read_b128 v[194:197], v157 offset:34816
	ds_read_b128 v[198:201], v157 offset:35840
	ds_read_b128 v[202:205], v157 offset:36864
	ds_read_b128 v[206:209], v157 offset:37888
	ds_read_b128 v[210:213], v157 offset:38912
	ds_read_b128 v[214:217], v157 offset:39936
	global_load_lds_dwordx4 v[226:227], off
	v_lshl_add_u64 v[226:227], s[28:29], 0, v[130:131]
	s_mov_b32 m0, s36
	s_nop 0
	global_load_lds_dwordx4 v[226:227], off
	s_waitcnt vmcnt(8) lgkmcnt(0)
	s_barrier
	s_setprio 1
	v_mfma_f32_16x16x32_bf16 v[124:127], v[144:147], v[186:189], v[124:127]
	v_mfma_f32_16x16x32_bf16 v[120:123], v[162:165], v[186:189], v[120:123]
	v_mfma_f32_16x16x32_bf16 v[116:119], v[144:147], v[194:197], v[116:119]
	v_mfma_f32_16x16x32_bf16 v[112:115], v[162:165], v[194:197], v[112:115]
	v_mfma_f32_16x16x32_bf16 v[104:107], v[144:147], v[202:205], v[104:107]
	v_mfma_f32_16x16x32_bf16 v[96:99], v[162:165], v[202:205], v[96:99]
	v_mfma_f32_16x16x32_bf16 v[76:79], v[144:147], v[210:213], v[76:79]
	v_mfma_f32_16x16x32_bf16 v[72:75], v[162:165], v[210:213], v[72:75]
	v_mfma_f32_16x16x32_bf16 v[124:127], v[158:161], v[190:193], v[124:127]
	v_mfma_f32_16x16x32_bf16 v[120:123], v[166:169], v[190:193], v[120:123]
	v_mfma_f32_16x16x32_bf16 v[116:119], v[158:161], v[198:201], v[116:119]
	v_mfma_f32_16x16x32_bf16 v[112:115], v[166:169], v[198:201], v[112:115]
	v_mfma_f32_16x16x32_bf16 v[104:107], v[158:161], v[206:209], v[104:107]
	v_mfma_f32_16x16x32_bf16 v[96:99], v[166:169], v[206:209], v[96:99]
	v_mfma_f32_16x16x32_bf16 v[76:79], v[158:161], v[214:217], v[76:79]
	v_mfma_f32_16x16x32_bf16 v[72:75], v[166:169], v[214:217], v[72:75]
	s_setprio 0
	s_setprio 1
	v_mfma_f32_16x16x32_bf16 v[108:111], v[170:173], v[186:189], v[108:111]
	v_mfma_f32_16x16x32_bf16 v[100:103], v[178:181], v[186:189], v[100:103]
	v_mfma_f32_16x16x32_bf16 v[92:95], v[170:173], v[194:197], v[92:95]
	v_mfma_f32_16x16x32_bf16 v[88:91], v[178:181], v[194:197], v[88:91]
	v_mfma_f32_16x16x32_bf16 v[84:87], v[170:173], v[202:205], v[84:87]
	v_mfma_f32_16x16x32_bf16 v[80:83], v[178:181], v[202:205], v[80:83]
	v_mfma_f32_16x16x32_bf16 v[68:71], v[170:173], v[210:213], v[68:71]
	v_mfma_f32_16x16x32_bf16 v[64:67], v[178:181], v[210:213], v[64:67]
	v_mfma_f32_16x16x32_bf16 v[108:111], v[174:177], v[190:193], v[108:111]
	v_mfma_f32_16x16x32_bf16 v[100:103], v[182:185], v[190:193], v[100:103]
	v_mfma_f32_16x16x32_bf16 v[92:95], v[174:177], v[198:201], v[92:95]
	v_mfma_f32_16x16x32_bf16 v[88:91], v[182:185], v[198:201], v[88:91]
	v_mfma_f32_16x16x32_bf16 v[84:87], v[174:177], v[206:209], v[84:87]
	v_mfma_f32_16x16x32_bf16 v[80:83], v[182:185], v[206:209], v[80:83]
	v_mfma_f32_16x16x32_bf16 v[68:71], v[174:177], v[214:217], v[68:71]
	v_mfma_f32_16x16x32_bf16 v[64:67], v[182:185], v[214:217], v[64:67]
	s_setprio 0
	s_barrier
; #define PG8_STAGE(bufoff, gbase, voff) do { _Pragma("unroll") for (int _i = 0; _i < 2; ++_i) \
;         __builtin_amdgcn_global_load_lds((const unsigned*)((const char*)(gbase) + (voff)[_i]), (PG8_LAS unsigned*)(lds + (bufoff) + ldsw + _i * 8192), 16, 0, 0); } while (0)
; #define PG8_LDA(dst, b, h) do { _Pragma("unroll") for (int m = 0; m < 4; ++m) _Pragma("unroll") for (int k = 0; k < 2; ++k) dst[m][k] = *(const PG8_LAS bf16x8*)(lds + PG8_SA(b, h) + aoff + m * 2048 + k * 1024); } while (0)
; #define PG8_MMA(ai, bj, At, Bt) do { __builtin_amdgcn_s_setprio(1); _Pragma("unroll") for (int m = 0; m < 4; ++m) _Pragma("unroll") for (int n = 0; n < 2; ++n) _Pragma("unroll") for (int k = 0; k < 2; ++k) \
;         acc[ai][bj][m][n] = __builtin_amdgcn_mfma_f32_16x16x32_bf16(Bt[n][k], At[m][k], acc[ai][bj][m][n], 0, 0, 0); __builtin_amdgcn_s_setprio(0); } while (0)
; #define PG8_WAIT_V(n) asm volatile("s_waitcnt vmcnt(" #n ")" ::: "memory")
; #define PG8_WAIT_L(n) asm volatile("s_waitcnt lgkmcnt(" #n ")" ::: "memory")
; #define PG8_BAR __builtin_amdgcn_s_barrier()
; #define PG8_SCHED __builtin_amdgcn_sched_barrier(0)
; template <class Epi, class Sched, bool ALIGN_EPI = false, bool SP2 = false>
; __device__ __forceinline__ void gemm_phase(PG8_LAS unsigned char* lds, const Gemm g, const Sched& S, const Epi& E) {
;     ...
;             PG8_LDA(At, 1, 1); PG8_STAGE(PG8_SB(1, 0), b3, voffB); PG8_STAGE(PG8_SB(1, 1), b3 + hstep, voffB); PG8_STAGE(PG8_SA(1, 0), a3, voffA);
;             PG8_WAIT_V(8); PG8_WAIT_L(0); PG8_BAR; PG8_MMA(1, 0, At, B0); PG8_MMA(1, 1, At, B1); PG8_BAR; PG8_SCHED;
;     ...
;         if constexpr (ALIGN_EPI) { if (wr == 0) PG8_BAR; }
	s_add_i32 s28, s51, s30
	v_lshl_add_u64 v[218:219], v[218:219], 0, s[8:9]
	s_mov_b32 m0, s28
	ds_read_b128 v[186:189], v157 offset:49152
	ds_read_b128 v[190:193], v157 offset:50176
	ds_read_b128 v[194:197], v157 offset:51200
	ds_read_b128 v[198:201], v157 offset:52224
	ds_read_b128 v[202:205], v157 offset:53248
	ds_read_b128 v[206:209], v157 offset:54272
	ds_read_b128 v[210:213], v157 offset:55296
	ds_read_b128 v[214:217], v157 offset:56320
	global_load_lds_dwordx4 v[218:219], off
	s_add_i32 m0, s28, 0x2000
	s_add_u32 s26, s26, 0x40080
	v_lshl_add_u64 v[218:219], v[220:221], 0, s[8:9]
	s_addc_u32 s27, s27, 0
	s_add_i32 s28, s52, s30
	global_load_lds_dwordx4 v[218:219], off
	v_lshl_add_u64 v[218:219], s[26:27], 0, v[132:133]
	s_mov_b32 m0, s28
	s_nop 0
	global_load_lds_dwordx4 v[218:219], off
	v_lshl_add_u64 v[218:219], s[26:27], 0, v[128:129]
	s_add_i32 m0, s28, 0x2000
	s_nop 0
	global_load_lds_dwordx4 v[218:219], off
	v_lshl_add_u64 v[218:219], v[222:223], 0, s[8:9]
	s_mov_b32 m0, s38
	s_nop 0
	global_load_lds_dwordx4 v[218:219], off
	v_lshl_add_u64 v[218:219], v[224:225], 0, s[8:9]
	s_mov_b32 m0, s39
	s_nop 0
	global_load_lds_dwordx4 v[218:219], off
	s_waitcnt vmcnt(8) lgkmcnt(0)
	s_barrier
	s_setprio 1
	v_mfma_f32_16x16x32_bf16 v[60:63], v[144:147], v[186:189], v[60:63]
	v_mfma_f32_16x16x32_bf16 v[56:59], v[162:165], v[186:189], v[56:59]
	v_mfma_f32_16x16x32_bf16 v[48:51], v[144:147], v[194:197], v[48:51]
	v_mfma_f32_16x16x32_bf16 v[40:43], v[162:165], v[194:197], v[40:43]
	v_mfma_f32_16x16x32_bf16 v[32:35], v[144:147], v[202:205], v[32:35]
	v_mfma_f32_16x16x32_bf16 v[24:27], v[162:165], v[202:205], v[24:27]
	v_mfma_f32_16x16x32_bf16 v[16:19], v[144:147], v[210:213], v[16:19]
	v_mfma_f32_16x16x32_bf16 v[8:11], v[162:165], v[210:213], v[8:11]
	v_mfma_f32_16x16x32_bf16 v[60:63], v[158:161], v[190:193], v[60:63]
	v_mfma_f32_16x16x32_bf16 v[56:59], v[166:169], v[190:193], v[56:59]
	v_mfma_f32_16x16x32_bf16 v[48:51], v[158:161], v[198:201], v[48:51]
	v_mfma_f32_16x16x32_bf16 v[40:43], v[166:169], v[198:201], v[40:43]
	v_mfma_f32_16x16x32_bf16 v[32:35], v[158:161], v[206:209], v[32:35]
	v_mfma_f32_16x16x32_bf16 v[24:27], v[166:169], v[206:209], v[24:27]
	v_mfma_f32_16x16x32_bf16 v[16:19], v[158:161], v[214:217], v[16:19]
	v_mfma_f32_16x16x32_bf16 v[8:11], v[166:169], v[214:217], v[8:11]
	s_setprio 0
	s_setprio 1
	v_mfma_f32_16x16x32_bf16 v[52:55], v[170:173], v[186:189], v[52:55]
	v_mfma_f32_16x16x32_bf16 v[44:47], v[178:181], v[186:189], v[44:47]
	v_mfma_f32_16x16x32_bf16 v[36:39], v[170:173], v[194:197], v[36:39]
	v_mfma_f32_16x16x32_bf16 v[28:31], v[178:181], v[194:197], v[28:31]
	v_mfma_f32_16x16x32_bf16 v[20:23], v[170:173], v[202:205], v[20:23]
	v_mfma_f32_16x16x32_bf16 v[12:15], v[178:181], v[202:205], v[12:15]
	v_mfma_f32_16x16x32_bf16 v[4:7], v[170:173], v[210:213], v[4:7]
	v_mfma_f32_16x16x32_bf16 v[0:3], v[178:181], v[210:213], v[0:3]
	v_mfma_f32_16x16x32_bf16 v[52:55], v[174:177], v[190:193], v[52:55]
	v_mfma_f32_16x16x32_bf16 v[44:47], v[182:185], v[190:193], v[44:47]
	v_mfma_f32_16x16x32_bf16 v[36:39], v[174:177], v[198:201], v[36:39]
	v_mfma_f32_16x16x32_bf16 v[28:31], v[182:185], v[198:201], v[28:31]
	v_mfma_f32_16x16x32_bf16 v[20:23], v[174:177], v[206:209], v[20:23]
	v_mfma_f32_16x16x32_bf16 v[12:15], v[182:185], v[206:209], v[12:15]
	v_mfma_f32_16x16x32_bf16 v[4:7], v[174:177], v[214:217], v[4:7]
	v_mfma_f32_16x16x32_bf16 v[0:3], v[182:185], v[214:217], v[0:3]
	s_setprio 0
	s_barrier
	s_add_i32 s50, s50, 2
	s_add_u32 s24, s24, 0x100
	s_addc_u32 s25, s25, 0
	s_add_u32 s48, s48, 0x100
	s_addc_u32 s49, s49, 0
	s_cmp_gt_u32 s50, 13
	s_cbranch_scc0 .LBB0_67
	s_and_b64 vcc, exec, s[10:11]
	s_cbranch_vccz .LBB0_70
	s_barrier

; #define PG8_STAGE(bufoff, gbase, voff) do { _Pragma("unroll") for (int _i = 0; _i < 2; ++_i) \
;         __builtin_amdgcn_global_load_lds((const unsigned*)((const char*)(gbase) + (voff)[_i]), (PG8_LAS unsigned*)(lds + (bufoff) + ldsw + _i * 8192), 16, 0, 0); } while (0)
; #define PG8_LDA(dst, b, h) do { _Pragma("unroll") for (int m = 0; m < 4; ++m) _Pragma("unroll") for (int k = 0; k < 2; ++k) dst[m][k] = *(const PG8_LAS bf16x8*)(lds + PG8_SA(b, h) + aoff + m * 2048 + k * 1024); } while (0)
; #define PG8_LDB(dst, b, h) do { _Pragma("unroll") for (int n = 0; n < 2; ++n) _Pragma("unroll") for (int k = 0; k < 2; ++k) dst[n][k] = *(const PG8_LAS bf16x8*)(lds + PG8_SB(b, h) + boff + n * 2048 + k * 1024); } while (0)
; #define PG8_MMA(ai, bj, At, Bt) do { __builtin_amdgcn_s_setprio(1); _Pragma("unroll") for (int m = 0; m < 4; ++m) _Pragma("unroll") for (int n = 0; n < 2; ++n) _Pragma("unroll") for (int k = 0; k < 2; ++k) \
;         acc[ai][bj][m][n] = __builtin_amdgcn_mfma_f32_16x16x32_bf16(Bt[n][k], At[m][k], acc[ai][bj][m][n], 0, 0, 0); __builtin_amdgcn_s_setprio(0); } while (0)
; #define PG8_WAIT_V(n) asm volatile("s_waitcnt vmcnt(" #n ")" ::: "memory")
; #define PG8_WAIT_L(n) asm volatile("s_waitcnt lgkmcnt(" #n ")" ::: "memory")
; #define PG8_BAR __builtin_amdgcn_s_barrier()
; #define PG8_SCHED __builtin_amdgcn_sched_barrier(0)
; template <class Epi, class Sched, bool ALIGN_EPI = false, bool SP2 = false>
; __device__ __forceinline__ void gemm_phase(PG8_LAS unsigned char* lds, const Gemm g, const Sched& S, const Epi& E) {
;     ...
;             PG8_LDB(B0, 0, 0); PG8_LDB(B1, 0, 1); PG8_SCHED; PG8_LDA(At, 0, 0); PG8_STAGE(PG8_SA(1, 1), a1 + hstep, voffA);
;             PG8_WAIT_V(8); PG8_WAIT_L(0); PG8_BAR; PG8_MMA(0, 0, At, B0); PG8_MMA(0, 1, At, B1); PG8_BAR; PG8_SCHED;
;             PG8_LDA(At, 0, 1); PG8_STAGE(PG8_SB(0, 0), b2, voffB); PG8_STAGE(PG8_SB(0, 1), b2 + hstep, voffB); PG8_STAGE(PG8_SA(0, 0), a2, voffA);
;             PG8_WAIT_V(8); PG8_WAIT_L(0); PG8_BAR; PG8_MMA(1, 0, At, B0); PG8_MMA(1, 1, At, B1); PG8_BAR; PG8_SCHED;
.LBB0_660:
	ds_read_b128 v[128:131], v191
	ds_read_b128 v[132:135], v191 offset:1024
	ds_read_b128 v[136:139], v191 offset:2048
	ds_read_b128 v[140:143], v191 offset:3072
	ds_read_b128 v[144:147], v192
	ds_read_b128 v[148:151], v192 offset:1024
	ds_read_b128 v[170:173], v192 offset:2048
	ds_read_b128 v[174:177], v192 offset:3072
	s_add_u32 s40, s38, 0xfffc0080
	s_addc_u32 s41, s39, -1
	s_cmp_eq_u32 s60, 12
	s_cselect_b32 s43, s29, s41
	s_cselect_b32 s42, s37, s40
	s_cselect_b32 s41, s27, s59
	s_cselect_b32 s40, s57, s58
	v_lshl_add_u64 v[186:187], s[38:39], 0, v[162:163]
	s_add_i32 m0, s44, 0xc000
	ds_read_b128 v[178:181], v193
	ds_read_b128 v[182:185], v193 offset:1024
	ds_read_b128 v[196:199], v193 offset:2048
	ds_read_b128 v[200:203], v193 offset:3072
	ds_read_b128 v[204:207], v193 offset:4096
	ds_read_b128 v[208:211], v193 offset:5120
	ds_read_b128 v[212:215], v193 offset:6144
	ds_read_b128 v[216:219], v193 offset:7168
	global_load_lds_dwordx4 v[186:187], off
	v_lshl_add_u64 v[186:187], s[38:39], 0, v[164:165]
	s_add_i32 m0, s44, 0xe000
	s_nop 0
	global_load_lds_dwordx4 v[186:187], off
	s_waitcnt vmcnt(8) lgkmcnt(0)
	s_barrier
	s_setprio 1
	v_mfma_f32_16x16x32_bf16 v[124:127], v[128:131], v[178:181], v[124:127]
	v_mfma_f32_16x16x32_bf16 v[120:123], v[136:139], v[178:181], v[120:123]
	v_mfma_f32_16x16x32_bf16 v[108:111], v[128:131], v[196:199], v[108:111]
	v_mfma_f32_16x16x32_bf16 v[104:107], v[136:139], v[196:199], v[104:107]
	v_mfma_f32_16x16x32_bf16 v[92:95], v[128:131], v[204:207], v[92:95]
	v_mfma_f32_16x16x32_bf16 v[88:91], v[136:139], v[204:207], v[88:91]
	v_mfma_f32_16x16x32_bf16 v[76:79], v[128:131], v[212:215], v[76:79]
	v_mfma_f32_16x16x32_bf16 v[72:75], v[136:139], v[212:215], v[72:75]
	v_mfma_f32_16x16x32_bf16 v[124:127], v[132:135], v[182:185], v[124:127]
	v_mfma_f32_16x16x32_bf16 v[120:123], v[140:143], v[182:185], v[120:123]
	v_mfma_f32_16x16x32_bf16 v[108:111], v[132:135], v[200:203], v[108:111]
	v_mfma_f32_16x16x32_bf16 v[104:107], v[140:143], v[200:203], v[104:107]
	v_mfma_f32_16x16x32_bf16 v[92:95], v[132:135], v[208:211], v[92:95]
	v_mfma_f32_16x16x32_bf16 v[88:91], v[140:143], v[208:211], v[88:91]
	v_mfma_f32_16x16x32_bf16 v[76:79], v[132:135], v[216:219], v[76:79]
	v_mfma_f32_16x16x32_bf16 v[72:75], v[140:143], v[216:219], v[72:75]
	s_setprio 0
	s_setprio 1
	v_mfma_f32_16x16x32_bf16 v[116:119], v[144:147], v[178:181], v[116:119]
	v_mfma_f32_16x16x32_bf16 v[112:115], v[170:173], v[178:181], v[112:115]
	v_mfma_f32_16x16x32_bf16 v[100:103], v[144:147], v[196:199], v[100:103]
	v_mfma_f32_16x16x32_bf16 v[96:99], v[170:173], v[196:199], v[96:99]
	v_mfma_f32_16x16x32_bf16 v[84:87], v[144:147], v[204:207], v[84:87]
	v_mfma_f32_16x16x32_bf16 v[80:83], v[170:173], v[204:207], v[80:83]
	v_mfma_f32_16x16x32_bf16 v[68:71], v[144:147], v[212:215], v[68:71]
	v_mfma_f32_16x16x32_bf16 v[64:67], v[170:173], v[212:215], v[64:67]
	v_mfma_f32_16x16x32_bf16 v[116:119], v[148:151], v[182:185], v[116:119]
	v_mfma_f32_16x16x32_bf16 v[112:115], v[174:177], v[182:185], v[112:115]
	v_mfma_f32_16x16x32_bf16 v[100:103], v[148:151], v[200:203], v[100:103]
	v_mfma_f32_16x16x32_bf16 v[96:99], v[174:177], v[200:203], v[96:99]
	v_mfma_f32_16x16x32_bf16 v[84:87], v[148:151], v[208:211], v[84:87]
	v_mfma_f32_16x16x32_bf16 v[80:83], v[174:177], v[208:211], v[80:83]
	v_mfma_f32_16x16x32_bf16 v[68:71], v[148:151], v[216:219], v[68:71]
	v_mfma_f32_16x16x32_bf16 v[64:67], v[174:177], v[216:219], v[64:67]
	s_setprio 0
	s_barrier
	s_add_i32 s61, s54, s33
	v_lshl_add_u64 v[186:187], s[40:41], 0, v[156:157]
	s_mov_b32 m0, s61
	ds_read_b128 v[178:181], v193 offset:16384
	ds_read_b128 v[182:185], v193 offset:17408
	ds_read_b128 v[196:199], v193 offset:18432
	ds_read_b128 v[200:203], v193 offset:19456
	ds_read_b128 v[204:207], v193 offset:20480
	ds_read_b128 v[208:211], v193 offset:21504
	ds_read_b128 v[212:215], v193 offset:22528
	ds_read_b128 v[216:219], v193 offset:23552
	global_load_lds_dwordx4 v[186:187], off
	s_add_i32 m0, s61, 0x2000
	s_add_u32 s62, s40, 0x40000
	v_lshl_add_u64 v[220:221], s[40:41], 0, v[160:161]
	s_addc_u32 s63, s41, 0
	s_add_i32 s61, s55, s33
	global_load_lds_dwordx4 v[220:221], off
	v_lshl_add_u64 v[222:223], s[62:63], 0, v[156:157]
	s_mov_b32 m0, s61
	v_lshl_add_u64 v[224:225], s[42:43], 0, v[158:159]
	global_load_lds_dwordx4 v[222:223], off
	v_lshl_add_u64 v[222:223], s[62:63], 0, v[160:161]
	s_add_i32 m0, s61, 0x2000
	s_nop 0
	global_load_lds_dwordx4 v[222:223], off
	v_lshl_add_u64 v[222:223], s[42:43], 0, v[154:155]
	s_mov_b32 m0, s44
	s_nop 0
	global_load_lds_dwordx4 v[222:223], off
	s_mov_b32 m0, s45
	s_nop 0
	global_load_lds_dwordx4 v[224:225], off
	s_waitcnt vmcnt(8) lgkmcnt(0)
	s_barrier
; #define PG8_STAGE(bufoff, gbase, voff) do { _Pragma("unroll") for (int _i = 0; _i < 2; ++_i) \
;         __builtin_amdgcn_global_load_lds((const unsigned*)((const char*)(gbase) + (voff)[_i]), (PG8_LAS unsigned*)(lds + (bufoff) + ldsw + _i * 8192), 16, 0, 0); } while (0)
; #define PG8_LDA(dst, b, h) do { _Pragma("unroll") for (int m = 0; m < 4; ++m) _Pragma("unroll") for (int k = 0; k < 2; ++k) dst[m][k] = *(const PG8_LAS bf16x8*)(lds + PG8_SA(b, h) + aoff + m * 2048 + k * 1024); } while (0)
; #define PG8_LDB(dst, b, h) do { _Pragma("unroll") for (int n = 0; n < 2; ++n) _Pragma("unroll") for (int k = 0; k < 2; ++k) dst[n][k] = *(const PG8_LAS bf16x8*)(lds + PG8_SB(b, h) + boff + n * 2048 + k * 1024); } while (0)
; #define PG8_MMA(ai, bj, At, Bt) do { __builtin_amdgcn_s_setprio(1); _Pragma("unroll") for (int m = 0; m < 4; ++m) _Pragma("unroll") for (int n = 0; n < 2; ++n) _Pragma("unroll") for (int k = 0; k < 2; ++k) \
;         acc[ai][bj][m][n] = __builtin_amdgcn_mfma_f32_16x16x32_bf16(Bt[n][k], At[m][k], acc[ai][bj][m][n], 0, 0, 0); __builtin_amdgcn_s_setprio(0); } while (0)
; #define PG8_WAIT_V(n) asm volatile("s_waitcnt vmcnt(" #n ")" ::: "memory")
; #define PG8_WAIT_L(n) asm volatile("s_waitcnt lgkmcnt(" #n ")" ::: "memory")
; #define PG8_BAR __builtin_amdgcn_s_barrier()
; #define PG8_SCHED __builtin_amdgcn_sched_barrier(0)
; template <class Epi, class Sched, bool ALIGN_EPI = false, bool SP2 = false>
; __device__ __forceinline__ void gemm_phase(PG8_LAS unsigned char* lds, const Gemm g, const Sched& S, const Epi& E) {
;     ...
;             PG8_WAIT_V(8); PG8_WAIT_L(0); PG8_BAR; PG8_MMA(1, 0, At, B0); PG8_MMA(1, 1, At, B1); PG8_BAR; PG8_SCHED;
;             PG8_LDB(B0, 1, 0); PG8_LDB(B1, 1, 1); PG8_SCHED; PG8_LDA(At, 1, 0); PG8_STAGE(PG8_SA(0, 1), a2 + hstep, voffA);
;             PG8_WAIT_V(8); PG8_WAIT_L(0); PG8_BAR; PG8_MMA(0, 0, At, B0); PG8_MMA(0, 1, At, B1); PG8_BAR; PG8_SCHED;
	s_setprio 1
	v_mfma_f32_16x16x32_bf16 v[60:63], v[128:131], v[178:181], v[60:63]
	v_mfma_f32_16x16x32_bf16 v[56:59], v[136:139], v[178:181], v[56:59]
	v_mfma_f32_16x16x32_bf16 v[44:47], v[128:131], v[196:199], v[44:47]
	v_mfma_f32_16x16x32_bf16 v[40:43], v[136:139], v[196:199], v[40:43]
	v_mfma_f32_16x16x32_bf16 v[28:31], v[128:131], v[204:207], v[28:31]
	v_mfma_f32_16x16x32_bf16 v[24:27], v[136:139], v[204:207], v[24:27]
	v_mfma_f32_16x16x32_bf16 v[12:15], v[128:131], v[212:215], v[12:15]
	v_mfma_f32_16x16x32_bf16 v[8:11], v[136:139], v[212:215], v[8:11]
	v_mfma_f32_16x16x32_bf16 v[60:63], v[132:135], v[182:185], v[60:63]
	v_mfma_f32_16x16x32_bf16 v[56:59], v[140:143], v[182:185], v[56:59]
	v_mfma_f32_16x16x32_bf16 v[44:47], v[132:135], v[200:203], v[44:47]
	v_mfma_f32_16x16x32_bf16 v[40:43], v[140:143], v[200:203], v[40:43]
	v_mfma_f32_16x16x32_bf16 v[28:31], v[132:135], v[208:211], v[28:31]
	v_mfma_f32_16x16x32_bf16 v[24:27], v[140:143], v[208:211], v[24:27]
	v_mfma_f32_16x16x32_bf16 v[12:15], v[132:135], v[216:219], v[12:15]
	v_mfma_f32_16x16x32_bf16 v[8:11], v[140:143], v[216:219], v[8:11]
	s_setprio 0
	s_setprio 1
	v_mfma_f32_16x16x32_bf16 v[52:55], v[144:147], v[178:181], v[52:55]
	v_mfma_f32_16x16x32_bf16 v[48:51], v[170:173], v[178:181], v[48:51]
	v_mfma_f32_16x16x32_bf16 v[36:39], v[144:147], v[196:199], v[36:39]
	v_mfma_f32_16x16x32_bf16 v[32:35], v[170:173], v[196:199], v[32:35]
	v_mfma_f32_16x16x32_bf16 v[20:23], v[144:147], v[204:207], v[20:23]
	v_mfma_f32_16x16x32_bf16 v[16:19], v[170:173], v[204:207], v[16:19]
	v_mfma_f32_16x16x32_bf16 v[4:7], v[144:147], v[212:215], v[4:7]
	v_mfma_f32_16x16x32_bf16 v[0:3], v[170:173], v[212:215], v[0:3]
	v_mfma_f32_16x16x32_bf16 v[52:55], v[148:151], v[182:185], v[52:55]
	v_mfma_f32_16x16x32_bf16 v[48:51], v[174:177], v[182:185], v[48:51]
	v_mfma_f32_16x16x32_bf16 v[36:39], v[148:151], v[200:203], v[36:39]
	v_mfma_f32_16x16x32_bf16 v[32:35], v[174:177], v[200:203], v[32:35]
	v_mfma_f32_16x16x32_bf16 v[20:23], v[148:151], v[208:211], v[20:23]
	v_mfma_f32_16x16x32_bf16 v[16:19], v[174:177], v[208:211], v[16:19]
	v_mfma_f32_16x16x32_bf16 v[4:7], v[148:151], v[216:219], v[4:7]
	v_mfma_f32_16x16x32_bf16 v[0:3], v[174:177], v[216:219], v[0:3]
	s_setprio 0
	s_barrier
	s_add_i32 s61, 0, 0x18000
	s_add_i32 s62, 0, 0x1c000
	v_add_u32_e32 v140, s61, v189
	v_add_u32_e32 v174, s62, v189
	ds_read_b128 v[128:131], v140
	ds_read_b128 v[132:135], v140 offset:1024
	ds_read_b128 v[136:139], v140 offset:2048
	ds_read_b128 v[140:143], v140 offset:3072
	ds_read_b128 v[144:147], v174
	ds_read_b128 v[148:151], v174 offset:1024
	ds_read_b128 v[170:173], v174 offset:2048
	ds_read_b128 v[174:177], v174 offset:3072
	s_add_u32 s42, s42, 0x40000
	s_addc_u32 s43, s43, 0
	s_mov_b32 m0, s46
	v_lshl_add_u64 v[226:227], s[42:43], 0, v[154:155]
	ds_read_b128 v[178:181], v193 offset:32768
	ds_read_b128 v[182:185], v193 offset:33792
	ds_read_b128 v[196:199], v193 offset:34816
	ds_read_b128 v[200:203], v193 offset:35840
	ds_read_b128 v[204:207], v193 offset:36864
	ds_read_b128 v[208:211], v193 offset:37888
	ds_read_b128 v[212:215], v193 offset:38912
	ds_read_b128 v[216:219], v193 offset:39936
	global_load_lds_dwordx4 v[226:227], off
	v_lshl_add_u64 v[226:227], s[42:43], 0, v[158:159]
	s_mov_b32 m0, s47
	s_nop 0
	global_load_lds_dwordx4 v[226:227], off
	s_waitcnt vmcnt(8) lgkmcnt(0)
	s_barrier
	s_setprio 1
	v_mfma_f32_16x16x32_bf16 v[124:127], v[128:131], v[178:181], v[124:127]
	v_mfma_f32_16x16x32_bf16 v[120:123], v[136:139], v[178:181], v[120:123]
	v_mfma_f32_16x16x32_bf16 v[108:111], v[128:131], v[196:199], v[108:111]
	v_mfma_f32_16x16x32_bf16 v[104:107], v[136:139], v[196:199], v[104:107]
	v_mfma_f32_16x16x32_bf16 v[92:95], v[128:131], v[204:207], v[92:95]
	v_mfma_f32_16x16x32_bf16 v[88:91], v[136:139], v[204:207], v[88:91]
	v_mfma_f32_16x16x32_bf16 v[76:79], v[128:131], v[212:215], v[76:79]
	v_mfma_f32_16x16x32_bf16 v[72:75], v[136:139], v[212:215], v[72:75]
	v_mfma_f32_16x16x32_bf16 v[124:127], v[132:135], v[182:185], v[124:127]
	v_mfma_f32_16x16x32_bf16 v[120:123], v[140:143], v[182:185], v[120:123]
	v_mfma_f32_16x16x32_bf16 v[108:111], v[132:135], v[200:203], v[108:111]
	v_mfma_f32_16x16x32_bf16 v[104:107], v[140:143], v[200:203], v[104:107]
	v_mfma_f32_16x16x32_bf16 v[92:95], v[132:135], v[208:211], v[92:95]
	v_mfma_f32_16x16x32_bf16 v[88:91], v[140:143], v[208:211], v[88:91]
	v_mfma_f32_16x16x32_bf16 v[76:79], v[132:135], v[216:219], v[76:79]
	v_mfma_f32_16x16x32_bf16 v[72:75], v[140:143], v[216:219], v[72:75]
	s_setprio 0
	s_setprio 1
	v_mfma_f32_16x16x32_bf16 v[116:119], v[144:147], v[178:181], v[116:119]
	v_mfma_f32_16x16x32_bf16 v[112:115], v[170:173], v[178:181], v[112:115]
	v_mfma_f32_16x16x32_bf16 v[100:103], v[144:147], v[196:199], v[100:103]
	v_mfma_f32_16x16x32_bf16 v[96:99], v[170:173], v[196:199], v[96:99]
	v_mfma_f32_16x16x32_bf16 v[84:87], v[144:147], v[204:207], v[84:87]
	v_mfma_f32_16x16x32_bf16 v[80:83], v[170:173], v[204:207], v[80:83]
	v_mfma_f32_16x16x32_bf16 v[68:71], v[144:147], v[212:215], v[68:71]
	v_mfma_f32_16x16x32_bf16 v[64:67], v[170:173], v[212:215], v[64:67]
	v_mfma_f32_16x16x32_bf16 v[116:119], v[148:151], v[182:185], v[116:119]
	v_mfma_f32_16x16x32_bf16 v[112:115], v[174:177], v[182:185], v[112:115]
	v_mfma_f32_16x16x32_bf16 v[100:103], v[148:151], v[200:203], v[100:103]
	v_mfma_f32_16x16x32_bf16 v[96:99], v[174:177], v[200:203], v[96:99]
	v_mfma_f32_16x16x32_bf16 v[84:87], v[148:151], v[208:211], v[84:87]
	v_mfma_f32_16x16x32_bf16 v[80:83], v[174:177], v[208:211], v[80:83]
	v_mfma_f32_16x16x32_bf16 v[68:71], v[148:151], v[216:219], v[68:71]
	v_mfma_f32_16x16x32_bf16 v[64:67], v[174:177], v[216:219], v[64:67]
	s_setprio 0
	s_barrier
; #define PG8_STAGE(bufoff, gbase, voff) do { _Pragma("unroll") for (int _i = 0; _i < 2; ++_i) \
;         __builtin_amdgcn_global_load_lds((const unsigned*)((const char*)(gbase) + (voff)[_i]), (PG8_LAS unsigned*)(lds + (bufoff) + ldsw + _i * 8192), 16, 0, 0); } while (0)
; #define PG8_LDA(dst, b, h) do { _Pragma("unroll") for (int m = 0; m < 4; ++m) _Pragma("unroll") for (int k = 0; k < 2; ++k) dst[m][k] = *(const PG8_LAS bf16x8*)(lds + PG8_SA(b, h) + aoff + m * 2048 + k * 1024); } while (0)
; #define PG8_MMA(ai, bj, At, Bt) do { __builtin_amdgcn_s_setprio(1); _Pragma("unroll") for (int m = 0; m < 4; ++m) _Pragma("unroll") for (int n = 0; n < 2; ++n) _Pragma("unroll") for (int k = 0; k < 2; ++k) \
;         acc[ai][bj][m][n] = __builtin_amdgcn_mfma_f32_16x16x32_bf16(Bt[n][k], At[m][k], acc[ai][bj][m][n], 0, 0, 0); __builtin_amdgcn_s_setprio(0); } while (0)
; #define PG8_WAIT_V(n) asm volatile("s_waitcnt vmcnt(" #n ")" ::: "memory")
; #define PG8_WAIT_L(n) asm volatile("s_waitcnt lgkmcnt(" #n ")" ::: "memory")
; #define PG8_BAR __builtin_amdgcn_s_barrier()
; #define PG8_SCHED __builtin_amdgcn_sched_barrier(0)
; template <class Epi, class Sched, bool ALIGN_EPI = false, bool SP2 = false>
; __device__ __forceinline__ void gemm_phase(PG8_LAS unsigned char* lds, const Gemm g, const Sched& S, const Epi& E) {
;     ...
;             PG8_LDA(At, 1, 1); PG8_STAGE(PG8_SB(1, 0), b3, voffB); PG8_STAGE(PG8_SB(1, 1), b3 + hstep, voffB); PG8_STAGE(PG8_SA(1, 0), a3, voffA);
;             PG8_WAIT_V(8); PG8_WAIT_L(0); PG8_BAR; PG8_MMA(1, 0, At, B0); PG8_MMA(1, 1, At, B1); PG8_BAR; PG8_SCHED;
;     ...
;         if constexpr (ALIGN_EPI) { if (wr == 0) PG8_BAR; }
	s_add_i32 s42, s61, s33
	v_lshl_add_u64 v[186:187], v[186:187], 0, s[22:23]
	s_mov_b32 m0, s42
	ds_read_b128 v[178:181], v193 offset:49152
	ds_read_b128 v[182:185], v193 offset:50176
	ds_read_b128 v[196:199], v193 offset:51200
	ds_read_b128 v[200:203], v193 offset:52224
	ds_read_b128 v[204:207], v193 offset:53248
	ds_read_b128 v[208:211], v193 offset:54272
	ds_read_b128 v[212:215], v193 offset:55296
	ds_read_b128 v[216:219], v193 offset:56320
	global_load_lds_dwordx4 v[186:187], off
	s_add_i32 m0, s42, 0x2000
	s_add_u32 s40, s40, 0x40080
	v_lshl_add_u64 v[186:187], v[220:221], 0, s[22:23]
	s_addc_u32 s41, s41, 0
	s_add_i32 s42, s62, s33
	global_load_lds_dwordx4 v[186:187], off
	v_lshl_add_u64 v[186:187], s[40:41], 0, v[156:157]
	s_mov_b32 m0, s42
	s_nop 0
	global_load_lds_dwordx4 v[186:187], off
	v_lshl_add_u64 v[186:187], s[40:41], 0, v[160:161]
	s_add_i32 m0, s42, 0x2000
	s_nop 0
	global_load_lds_dwordx4 v[186:187], off
	v_lshl_add_u64 v[186:187], v[222:223], 0, s[22:23]
	s_mov_b32 m0, s49
	s_nop 0
	global_load_lds_dwordx4 v[186:187], off
	v_lshl_add_u64 v[186:187], v[224:225], 0, s[22:23]
	s_mov_b32 m0, s50
	s_nop 0
	global_load_lds_dwordx4 v[186:187], off
	s_waitcnt vmcnt(8) lgkmcnt(0)
	s_barrier
	s_setprio 1
	v_mfma_f32_16x16x32_bf16 v[60:63], v[128:131], v[178:181], v[60:63]
	v_mfma_f32_16x16x32_bf16 v[56:59], v[136:139], v[178:181], v[56:59]
	v_mfma_f32_16x16x32_bf16 v[44:47], v[128:131], v[196:199], v[44:47]
	v_mfma_f32_16x16x32_bf16 v[40:43], v[136:139], v[196:199], v[40:43]
	v_mfma_f32_16x16x32_bf16 v[28:31], v[128:131], v[204:207], v[28:31]
	v_mfma_f32_16x16x32_bf16 v[24:27], v[136:139], v[204:207], v[24:27]
	v_mfma_f32_16x16x32_bf16 v[12:15], v[128:131], v[212:215], v[12:15]
	v_mfma_f32_16x16x32_bf16 v[8:11], v[136:139], v[212:215], v[8:11]
	v_mfma_f32_16x16x32_bf16 v[60:63], v[132:135], v[182:185], v[60:63]
	v_mfma_f32_16x16x32_bf16 v[56:59], v[140:143], v[182:185], v[56:59]
	v_mfma_f32_16x16x32_bf16 v[44:47], v[132:135], v[200:203], v[44:47]
	v_mfma_f32_16x16x32_bf16 v[40:43], v[140:143], v[200:203], v[40:43]
	v_mfma_f32_16x16x32_bf16 v[28:31], v[132:135], v[208:211], v[28:31]
	v_mfma_f32_16x16x32_bf16 v[24:27], v[140:143], v[208:211], v[24:27]
	v_mfma_f32_16x16x32_bf16 v[12:15], v[132:135], v[216:219], v[12:15]
	v_mfma_f32_16x16x32_bf16 v[8:11], v[140:143], v[216:219], v[8:11]
	s_setprio 0
	s_setprio 1
	v_mfma_f32_16x16x32_bf16 v[52:55], v[144:147], v[178:181], v[52:55]
	v_mfma_f32_16x16x32_bf16 v[48:51], v[170:173], v[178:181], v[48:51]
	v_mfma_f32_16x16x32_bf16 v[36:39], v[144:147], v[196:199], v[36:39]
	v_mfma_f32_16x16x32_bf16 v[32:35], v[170:173], v[196:199], v[32:35]
	v_mfma_f32_16x16x32_bf16 v[20:23], v[144:147], v[204:207], v[20:23]
	v_mfma_f32_16x16x32_bf16 v[16:19], v[170:173], v[204:207], v[16:19]
	v_mfma_f32_16x16x32_bf16 v[4:7], v[144:147], v[212:215], v[4:7]
	v_mfma_f32_16x16x32_bf16 v[0:3], v[170:173], v[212:215], v[0:3]
	v_mfma_f32_16x16x32_bf16 v[52:55], v[148:151], v[182:185], v[52:55]
	v_mfma_f32_16x16x32_bf16 v[48:51], v[174:177], v[182:185], v[48:51]
	v_mfma_f32_16x16x32_bf16 v[36:39], v[148:151], v[200:203], v[36:39]
	v_mfma_f32_16x16x32_bf16 v[32:35], v[174:177], v[200:203], v[32:35]
	v_mfma_f32_16x16x32_bf16 v[20:23], v[148:151], v[208:211], v[20:23]
	v_mfma_f32_16x16x32_bf16 v[16:19], v[174:177], v[208:211], v[16:19]
	v_mfma_f32_16x16x32_bf16 v[4:7], v[148:151], v[216:219], v[4:7]
	v_mfma_f32_16x16x32_bf16 v[0:3], v[174:177], v[216:219], v[0:3]
	s_setprio 0
	s_barrier
	s_add_i32 s60, s60, 2
	s_add_u32 s38, s38, 0x100
	s_addc_u32 s39, s39, 0
	s_add_u32 s58, s58, 0x100
	s_addc_u32 s59, s59, 0
	s_cmp_gt_u32 s60, 13
	s_cbranch_scc0 .LBB0_660
	s_and_b64 vcc, exec, s[24:25]
	s_cbranch_vccz .LBB0_663
	s_barrier

; #define PG8_STAGE(bufoff, gbase, voff) do { _Pragma("unroll") for (int _i = 0; _i < 2; ++_i) \
;         __builtin_amdgcn_global_load_lds((const unsigned*)((const char*)(gbase) + (voff)[_i]), (PG8_LAS unsigned*)(lds + (bufoff) + ldsw + _i * 8192), 16, 0, 0); } while (0)
; #define PG8_LDA(dst, b, h) do { _Pragma("unroll") for (int m = 0; m < 4; ++m) _Pragma("unroll") for (int k = 0; k < 2; ++k) dst[m][k] = *(const PG8_LAS bf16x8*)(lds + PG8_SA(b, h) + aoff + m * 2048 + k * 1024); } while (0)
; #define PG8_LDB(dst, b, h) do { _Pragma("unroll") for (int n = 0; n < 2; ++n) _Pragma("unroll") for (int k = 0; k < 2; ++k) dst[n][k] = *(const PG8_LAS bf16x8*)(lds + PG8_SB(b, h) + boff + n * 2048 + k * 1024); } while (0)
; #define PG8_MMA(ai, bj, At, Bt) do { __builtin_amdgcn_s_setprio(1); _Pragma("unroll") for (int m = 0; m < 4; ++m) _Pragma("unroll") for (int n = 0; n < 2; ++n) _Pragma("unroll") for (int k = 0; k < 2; ++k) \
;         acc[ai][bj][m][n] = __builtin_amdgcn_mfma_f32_16x16x32_bf16(Bt[n][k], At[m][k], acc[ai][bj][m][n], 0, 0, 0); __builtin_amdgcn_s_setprio(0); } while (0)
; #define PG8_WAIT_V(n) asm volatile("s_waitcnt vmcnt(" #n ")" ::: "memory")
; #define PG8_BAR __builtin_amdgcn_s_barrier()
; template <class Epi, class Sched, bool ALIGN_EPI = false, bool SP2 = false>
; __device__ __forceinline__ void gemm_phase(PG8_LAS unsigned char* lds, const Gemm g, const Sched& S, const Epi& E) {
;     ...
;         for (int t = 0; t < nt; t += 2) {
;             const bool last = (t == nt - 2);
;             const char* a1 = cA + (size_t)(t + 1) * kstep;
;             const char* a2 = last ? nA : cA + (size_t)(t + 2) * kstep; const char* b2 = last ? nB : cB + (size_t)(t + 2) * kstep;
;             const char* a3 = a2 + kstep; const char* b3 = b2 + kstep;
;             if (last && has_next) S.a_ready(nxt);
;             if constexpr (SP2) {
;             PG8_LDB(B0, 0, 0); PG8_LDB(B1, 0, 1); PG8_SCHED; PG8_LDA(At, 0, 0); PG8_STAGE(PG8_SA(1, 1), a1 + hstep, voffA);
;             PG8_WAIT_V(8); PG8_WAIT_L(0); PG8_BAR; PG8_MMA(0, 0, At, B0); PG8_MMA(0, 1, At, B1); PG8_BAR; PG8_SCHED;
;             PG8_LDA(At, 0, 1); PG8_STAGE(PG8_SB(0, 0), b2, voffB); PG8_STAGE(PG8_SB(0, 1), b2 + hstep, voffB); PG8_STAGE(PG8_SA(0, 0), a2, voffA);
;             PG8_WAIT_V(8); PG8_WAIT_L(0); PG8_BAR; PG8_MMA(1, 0, At, B0); PG8_MMA(1, 1, At, B1); PG8_BAR; PG8_SCHED;
.LBB0_745:
	ds_read_b128 v[148:151], v190
	ds_read_b128 v[154:157], v190 offset:1024
	ds_read_b128 v[158:161], v190 offset:2048
	ds_read_b128 v[162:165], v190 offset:3072
	ds_read_b128 v[172:175], v191
	ds_read_b128 v[176:179], v191 offset:1024
	ds_read_b128 v[180:183], v191 offset:2048
	ds_read_b128 v[196:199], v191 offset:3072
	s_add_u32 s10, s8, 0x100
	s_addc_u32 s11, s9, 0
	s_cmp_eq_u32 s71, 12
	s_cselect_b32 s49, s43, s11
	s_cselect_b32 s48, s67, s10
	s_cselect_b32 s13, s41, s70
	s_cselect_b32 s12, s68, s69
	v_lshl_add_u64 v[166:167], s[8:9], 0, v[140:141]
	s_add_i32 m0, s35, 0xc000
	ds_read_b128 v[200:203], v192
	ds_read_b128 v[204:207], v192 offset:1024
	ds_read_b128 v[208:211], v192 offset:2048
	ds_read_b128 v[212:215], v192 offset:3072
	ds_read_b128 v[216:219], v192 offset:4096
	ds_read_b128 v[220:223], v192 offset:5120
	ds_read_b128 v[224:227], v192 offset:6144
	ds_read_b128 v[228:231], v192 offset:7168
	global_load_lds_dwordx4 v[166:167], off
	v_lshl_add_u64 v[166:167], s[8:9], 0, v[142:143]
	s_add_i32 m0, s35, 0xe000
	s_nop 0
	global_load_lds_dwordx4 v[166:167], off
	s_waitcnt vmcnt(8) lgkmcnt(0)
	s_barrier
	s_setprio 1
	v_mfma_f32_16x16x32_bf16 v[124:127], v[148:151], v[200:203], v[124:127]
	v_mfma_f32_16x16x32_bf16 v[92:95], v[158:161], v[200:203], v[92:95]
	v_mfma_f32_16x16x32_bf16 v[120:123], v[148:151], v[208:211], v[120:123]
	v_mfma_f32_16x16x32_bf16 v[80:83], v[158:161], v[208:211], v[80:83]
	v_mfma_f32_16x16x32_bf16 v[116:119], v[148:151], v[216:219], v[116:119]
	v_mfma_f32_16x16x32_bf16 v[88:91], v[158:161], v[216:219], v[88:91]
	v_mfma_f32_16x16x32_bf16 v[112:115], v[148:151], v[224:227], v[112:115]
	v_mfma_f32_16x16x32_bf16 v[84:87], v[158:161], v[224:227], v[84:87]
	v_mfma_f32_16x16x32_bf16 v[124:127], v[154:157], v[204:207], v[124:127]
	v_mfma_f32_16x16x32_bf16 v[92:95], v[162:165], v[204:207], v[92:95]
	v_mfma_f32_16x16x32_bf16 v[120:123], v[154:157], v[212:215], v[120:123]
	v_mfma_f32_16x16x32_bf16 v[80:83], v[162:165], v[212:215], v[80:83]
	v_mfma_f32_16x16x32_bf16 v[116:119], v[154:157], v[220:223], v[116:119]
	v_mfma_f32_16x16x32_bf16 v[88:91], v[162:165], v[220:223], v[88:91]
	v_mfma_f32_16x16x32_bf16 v[112:115], v[154:157], v[228:231], v[112:115]
	v_mfma_f32_16x16x32_bf16 v[84:87], v[162:165], v[228:231], v[84:87]
	s_setprio 0
	s_setprio 1
	v_mfma_f32_16x16x32_bf16 v[108:111], v[172:175], v[200:203], v[108:111]
	v_mfma_f32_16x16x32_bf16 v[64:67], v[180:183], v[200:203], v[64:67]
	v_mfma_f32_16x16x32_bf16 v[104:107], v[172:175], v[208:211], v[104:107]
	v_mfma_f32_16x16x32_bf16 v[68:71], v[180:183], v[208:211], v[68:71]
	v_mfma_f32_16x16x32_bf16 v[100:103], v[172:175], v[216:219], v[100:103]
	v_mfma_f32_16x16x32_bf16 v[72:75], v[180:183], v[216:219], v[72:75]
	v_mfma_f32_16x16x32_bf16 v[96:99], v[172:175], v[224:227], v[96:99]
	v_mfma_f32_16x16x32_bf16 v[76:79], v[180:183], v[224:227], v[76:79]
	v_mfma_f32_16x16x32_bf16 v[108:111], v[176:179], v[204:207], v[108:111]
	v_mfma_f32_16x16x32_bf16 v[64:67], v[196:199], v[204:207], v[64:67]
	v_mfma_f32_16x16x32_bf16 v[104:107], v[176:179], v[212:215], v[104:107]
	v_mfma_f32_16x16x32_bf16 v[68:71], v[196:199], v[212:215], v[68:71]
	v_mfma_f32_16x16x32_bf16 v[100:103], v[176:179], v[220:223], v[100:103]
	v_mfma_f32_16x16x32_bf16 v[72:75], v[196:199], v[220:223], v[72:75]
	v_mfma_f32_16x16x32_bf16 v[96:99], v[176:179], v[228:231], v[96:99]
	v_mfma_f32_16x16x32_bf16 v[76:79], v[196:199], v[228:231], v[76:79]
	s_setprio 0
	s_barrier
	s_add_i32 s8, s61, s33
	v_lshl_add_u64 v[166:167], s[12:13], 0, v[132:133]
	s_mov_b32 m0, s8
	ds_read_b128 v[200:203], v192 offset:16384
	ds_read_b128 v[204:207], v192 offset:17408
	ds_read_b128 v[208:211], v192 offset:18432
	ds_read_b128 v[212:215], v192 offset:19456
	ds_read_b128 v[216:219], v192 offset:20480
	ds_read_b128 v[220:223], v192 offset:21504
	ds_read_b128 v[224:227], v192 offset:22528
	ds_read_b128 v[228:231], v192 offset:23552
	global_load_lds_dwordx4 v[166:167], off
	s_add_i32 m0, s8, 0x2000
	s_add_u32 s8, s12, 0x40000
	v_lshl_add_u64 v[184:185], s[12:13], 0, v[128:129]
	s_addc_u32 s9, s13, 0
	s_add_i32 s72, s62, s33
	global_load_lds_dwordx4 v[184:185], off
	v_lshl_add_u64 v[232:233], s[8:9], 0, v[132:133]
	s_mov_b32 m0, s72
	v_lshl_add_u64 v[234:235], s[48:49], 0, v[130:131]
	global_load_lds_dwordx4 v[232:233], off
	v_lshl_add_u64 v[232:233], s[8:9], 0, v[128:129]
	s_add_i32 m0, s72, 0x2000
	s_nop 0
	global_load_lds_dwordx4 v[232:233], off
	v_lshl_add_u64 v[232:233], s[48:49], 0, v[134:135]
	s_mov_b32 m0, s35
	s_nop 0
	global_load_lds_dwordx4 v[232:233], off
	s_mov_b32 m0, s74
	s_nop 0
	global_load_lds_dwordx4 v[234:235], off
	s_waitcnt vmcnt(8) lgkmcnt(0)
	s_barrier
; #define PG8_STAGE(bufoff, gbase, voff) do { _Pragma("unroll") for (int _i = 0; _i < 2; ++_i) \
;         __builtin_amdgcn_global_load_lds((const unsigned*)((const char*)(gbase) + (voff)[_i]), (PG8_LAS unsigned*)(lds + (bufoff) + ldsw + _i * 8192), 16, 0, 0); } while (0)
; #define PG8_LDA(dst, b, h) do { _Pragma("unroll") for (int m = 0; m < 4; ++m) _Pragma("unroll") for (int k = 0; k < 2; ++k) dst[m][k] = *(const PG8_LAS bf16x8*)(lds + PG8_SA(b, h) + aoff + m * 2048 + k * 1024); } while (0)
; #define PG8_LDB(dst, b, h) do { _Pragma("unroll") for (int n = 0; n < 2; ++n) _Pragma("unroll") for (int k = 0; k < 2; ++k) dst[n][k] = *(const PG8_LAS bf16x8*)(lds + PG8_SB(b, h) + boff + n * 2048 + k * 1024); } while (0)
; #define PG8_MMA(ai, bj, At, Bt) do { __builtin_amdgcn_s_setprio(1); _Pragma("unroll") for (int m = 0; m < 4; ++m) _Pragma("unroll") for (int n = 0; n < 2; ++n) _Pragma("unroll") for (int k = 0; k < 2; ++k) \
;         acc[ai][bj][m][n] = __builtin_amdgcn_mfma_f32_16x16x32_bf16(Bt[n][k], At[m][k], acc[ai][bj][m][n], 0, 0, 0); __builtin_amdgcn_s_setprio(0); } while (0)
; #define PG8_WAIT_V(n) asm volatile("s_waitcnt vmcnt(" #n ")" ::: "memory")
; #define PG8_WAIT_L(n) asm volatile("s_waitcnt lgkmcnt(" #n ")" ::: "memory")
; #define PG8_BAR __builtin_amdgcn_s_barrier()
; #define PG8_SCHED __builtin_amdgcn_sched_barrier(0)
; template <class Epi, class Sched, bool ALIGN_EPI = false, bool SP2 = false>
; __device__ __forceinline__ void gemm_phase(PG8_LAS unsigned char* lds, const Gemm g, const Sched& S, const Epi& E) {
;     ...
;             PG8_WAIT_V(8); PG8_WAIT_L(0); PG8_BAR; PG8_MMA(1, 0, At, B0); PG8_MMA(1, 1, At, B1); PG8_BAR; PG8_SCHED;
;             PG8_LDB(B0, 1, 0); PG8_LDB(B1, 1, 1); PG8_SCHED; PG8_LDA(At, 1, 0); PG8_STAGE(PG8_SA(0, 1), a2 + hstep, voffA);
;             PG8_WAIT_V(8); PG8_WAIT_L(0); PG8_BAR; PG8_MMA(0, 0, At, B0); PG8_MMA(0, 1, At, B1); PG8_BAR; PG8_SCHED;
	s_setprio 1
	v_mfma_f32_16x16x32_bf16 v[60:63], v[148:151], v[200:203], v[60:63]
	v_mfma_f32_16x16x32_bf16 v[16:19], v[158:161], v[200:203], v[16:19]
	v_mfma_f32_16x16x32_bf16 v[56:59], v[148:151], v[208:211], v[56:59]
	v_mfma_f32_16x16x32_bf16 v[20:23], v[158:161], v[208:211], v[20:23]
	v_mfma_f32_16x16x32_bf16 v[52:55], v[148:151], v[216:219], v[52:55]
	v_mfma_f32_16x16x32_bf16 v[24:27], v[158:161], v[216:219], v[24:27]
	v_mfma_f32_16x16x32_bf16 v[48:51], v[148:151], v[224:227], v[48:51]
	v_mfma_f32_16x16x32_bf16 v[28:31], v[158:161], v[224:227], v[28:31]
	v_mfma_f32_16x16x32_bf16 v[60:63], v[154:157], v[204:207], v[60:63]
	v_mfma_f32_16x16x32_bf16 v[16:19], v[162:165], v[204:207], v[16:19]
	v_mfma_f32_16x16x32_bf16 v[56:59], v[154:157], v[212:215], v[56:59]
	v_mfma_f32_16x16x32_bf16 v[20:23], v[162:165], v[212:215], v[20:23]
	v_mfma_f32_16x16x32_bf16 v[52:55], v[154:157], v[220:223], v[52:55]
	v_mfma_f32_16x16x32_bf16 v[24:27], v[162:165], v[220:223], v[24:27]
	v_mfma_f32_16x16x32_bf16 v[48:51], v[154:157], v[228:231], v[48:51]
	v_mfma_f32_16x16x32_bf16 v[28:31], v[162:165], v[228:231], v[28:31]
	s_setprio 0
	s_setprio 1
	v_mfma_f32_16x16x32_bf16 v[44:47], v[172:175], v[200:203], v[44:47]
	v_mfma_f32_16x16x32_bf16 v[0:3], v[180:183], v[200:203], v[0:3]
	v_mfma_f32_16x16x32_bf16 v[40:43], v[172:175], v[208:211], v[40:43]
	v_mfma_f32_16x16x32_bf16 v[4:7], v[180:183], v[208:211], v[4:7]
	v_mfma_f32_16x16x32_bf16 v[36:39], v[172:175], v[216:219], v[36:39]
	v_mfma_f32_16x16x32_bf16 v[8:11], v[180:183], v[216:219], v[8:11]
	v_mfma_f32_16x16x32_bf16 v[32:35], v[172:175], v[224:227], v[32:35]
	v_mfma_f32_16x16x32_bf16 v[12:15], v[180:183], v[224:227], v[12:15]
	v_mfma_f32_16x16x32_bf16 v[44:47], v[176:179], v[204:207], v[44:47]
	v_mfma_f32_16x16x32_bf16 v[0:3], v[196:199], v[204:207], v[0:3]
	v_mfma_f32_16x16x32_bf16 v[40:43], v[176:179], v[212:215], v[40:43]
	v_mfma_f32_16x16x32_bf16 v[4:7], v[196:199], v[212:215], v[4:7]
	v_mfma_f32_16x16x32_bf16 v[36:39], v[176:179], v[220:223], v[36:39]
	v_mfma_f32_16x16x32_bf16 v[8:11], v[196:199], v[220:223], v[8:11]
	v_mfma_f32_16x16x32_bf16 v[32:35], v[176:179], v[228:231], v[32:35]
	v_mfma_f32_16x16x32_bf16 v[12:15], v[196:199], v[228:231], v[12:15]
	s_setprio 0
	s_barrier
	s_add_i32 s72, 0, 0x18000
	s_add_i32 s73, 0, 0x1c000
	v_add_u32_e32 v162, s72, v171
	v_add_u32_e32 v168, s73, v171
	ds_read_b128 v[148:151], v162
	ds_read_b128 v[154:157], v162 offset:1024
	ds_read_b128 v[158:161], v162 offset:2048
	ds_read_b128 v[162:165], v162 offset:3072
	ds_read_b128 v[172:175], v168
	ds_read_b128 v[176:179], v168 offset:1024
	ds_read_b128 v[180:183], v168 offset:2048
	ds_read_b128 v[196:199], v168 offset:3072
	s_add_u32 s8, s48, 0x40000
	s_addc_u32 s9, s49, 0
	s_mov_b32 m0, s52
	v_lshl_add_u64 v[236:237], s[8:9], 0, v[134:135]
	ds_read_b128 v[200:203], v192 offset:32768
	ds_read_b128 v[204:207], v192 offset:33792
	ds_read_b128 v[208:211], v192 offset:34816
	ds_read_b128 v[212:215], v192 offset:35840
	ds_read_b128 v[216:219], v192 offset:36864
	ds_read_b128 v[220:223], v192 offset:37888
	ds_read_b128 v[224:227], v192 offset:38912
	ds_read_b128 v[228:231], v192 offset:39936
	global_load_lds_dwordx4 v[236:237], off
	v_lshl_add_u64 v[236:237], s[8:9], 0, v[130:131]
	s_mov_b32 m0, s53
	s_nop 0
	global_load_lds_dwordx4 v[236:237], off
	s_waitcnt vmcnt(8) lgkmcnt(0)
	s_barrier
	s_setprio 1
	v_mfma_f32_16x16x32_bf16 v[124:127], v[148:151], v[200:203], v[124:127]
	v_mfma_f32_16x16x32_bf16 v[92:95], v[158:161], v[200:203], v[92:95]
	v_mfma_f32_16x16x32_bf16 v[120:123], v[148:151], v[208:211], v[120:123]
	v_mfma_f32_16x16x32_bf16 v[80:83], v[158:161], v[208:211], v[80:83]
	v_mfma_f32_16x16x32_bf16 v[116:119], v[148:151], v[216:219], v[116:119]
	v_mfma_f32_16x16x32_bf16 v[88:91], v[158:161], v[216:219], v[88:91]
	v_mfma_f32_16x16x32_bf16 v[112:115], v[148:151], v[224:227], v[112:115]
	v_mfma_f32_16x16x32_bf16 v[84:87], v[158:161], v[224:227], v[84:87]
	v_mfma_f32_16x16x32_bf16 v[124:127], v[154:157], v[204:207], v[124:127]
	v_mfma_f32_16x16x32_bf16 v[92:95], v[162:165], v[204:207], v[92:95]
	v_mfma_f32_16x16x32_bf16 v[120:123], v[154:157], v[212:215], v[120:123]
	v_mfma_f32_16x16x32_bf16 v[80:83], v[162:165], v[212:215], v[80:83]
	v_mfma_f32_16x16x32_bf16 v[116:119], v[154:157], v[220:223], v[116:119]
	v_mfma_f32_16x16x32_bf16 v[88:91], v[162:165], v[220:223], v[88:91]
	v_mfma_f32_16x16x32_bf16 v[112:115], v[154:157], v[228:231], v[112:115]
	v_mfma_f32_16x16x32_bf16 v[84:87], v[162:165], v[228:231], v[84:87]
	s_setprio 0
	s_setprio 1
	v_mfma_f32_16x16x32_bf16 v[108:111], v[172:175], v[200:203], v[108:111]
	v_mfma_f32_16x16x32_bf16 v[64:67], v[180:183], v[200:203], v[64:67]
	v_mfma_f32_16x16x32_bf16 v[104:107], v[172:175], v[208:211], v[104:107]
	v_mfma_f32_16x16x32_bf16 v[68:71], v[180:183], v[208:211], v[68:71]
	v_mfma_f32_16x16x32_bf16 v[100:103], v[172:175], v[216:219], v[100:103]
	v_mfma_f32_16x16x32_bf16 v[72:75], v[180:183], v[216:219], v[72:75]
	v_mfma_f32_16x16x32_bf16 v[96:99], v[172:175], v[224:227], v[96:99]
	v_mfma_f32_16x16x32_bf16 v[76:79], v[180:183], v[224:227], v[76:79]
	v_mfma_f32_16x16x32_bf16 v[108:111], v[176:179], v[204:207], v[108:111]
	v_mfma_f32_16x16x32_bf16 v[64:67], v[196:199], v[204:207], v[64:67]
	v_mfma_f32_16x16x32_bf16 v[104:107], v[176:179], v[212:215], v[104:107]
	v_mfma_f32_16x16x32_bf16 v[68:71], v[196:199], v[212:215], v[68:71]
	v_mfma_f32_16x16x32_bf16 v[100:103], v[176:179], v[220:223], v[100:103]
	v_mfma_f32_16x16x32_bf16 v[72:75], v[196:199], v[220:223], v[72:75]
	v_mfma_f32_16x16x32_bf16 v[96:99], v[176:179], v[228:231], v[96:99]
	v_mfma_f32_16x16x32_bf16 v[76:79], v[196:199], v[228:231], v[76:79]
	s_setprio 0
	s_barrier
; #define PG8_STAGE(bufoff, gbase, voff) do { _Pragma("unroll") for (int _i = 0; _i < 2; ++_i) \
;         __builtin_amdgcn_global_load_lds((const unsigned*)((const char*)(gbase) + (voff)[_i]), (PG8_LAS unsigned*)(lds + (bufoff) + ldsw + _i * 8192), 16, 0, 0); } while (0)
; #define PG8_LDA(dst, b, h) do { _Pragma("unroll") for (int m = 0; m < 4; ++m) _Pragma("unroll") for (int k = 0; k < 2; ++k) dst[m][k] = *(const PG8_LAS bf16x8*)(lds + PG8_SA(b, h) + aoff + m * 2048 + k * 1024); } while (0)
; #define PG8_MMA(ai, bj, At, Bt) do { __builtin_amdgcn_s_setprio(1); _Pragma("unroll") for (int m = 0; m < 4; ++m) _Pragma("unroll") for (int n = 0; n < 2; ++n) _Pragma("unroll") for (int k = 0; k < 2; ++k) \
;         acc[ai][bj][m][n] = __builtin_amdgcn_mfma_f32_16x16x32_bf16(Bt[n][k], At[m][k], acc[ai][bj][m][n], 0, 0, 0); __builtin_amdgcn_s_setprio(0); } while (0)
; #define PG8_WAIT_V(n) asm volatile("s_waitcnt vmcnt(" #n ")" ::: "memory")
; #define PG8_WAIT_L(n) asm volatile("s_waitcnt lgkmcnt(" #n ")" ::: "memory")
; #define PG8_BAR __builtin_amdgcn_s_barrier()
; #define PG8_SCHED __builtin_amdgcn_sched_barrier(0)
; template <class Epi, class Sched, bool ALIGN_EPI = false, bool SP2 = false>
; __device__ __forceinline__ void gemm_phase(PG8_LAS unsigned char* lds, const Gemm g, const Sched& S, const Epi& E) {
;     ...
;             PG8_LDA(At, 1, 1); PG8_STAGE(PG8_SB(1, 0), b3, voffB); PG8_STAGE(PG8_SB(1, 1), b3 + hstep, voffB); PG8_STAGE(PG8_SA(1, 0), a3, voffA);
;             PG8_WAIT_V(8); PG8_WAIT_L(0); PG8_BAR; PG8_MMA(1, 0, At, B0); PG8_MMA(1, 1, At, B1); PG8_BAR; PG8_SCHED;
;     ...
;         if constexpr (ALIGN_EPI) { if (wr == 0) PG8_BAR; }
	s_add_i32 s8, s72, s33
	v_lshl_add_u64 v[166:167], v[166:167], 0, s[30:31]
	s_mov_b32 m0, s8
	ds_read_b128 v[200:203], v192 offset:49152
	ds_read_b128 v[204:207], v192 offset:50176
	ds_read_b128 v[208:211], v192 offset:51200
	ds_read_b128 v[212:215], v192 offset:52224
	ds_read_b128 v[216:219], v192 offset:53248
	ds_read_b128 v[220:223], v192 offset:54272
	ds_read_b128 v[224:227], v192 offset:55296
	ds_read_b128 v[228:231], v192 offset:56320
	global_load_lds_dwordx4 v[166:167], off
	s_add_i32 m0, s8, 0x2000
	s_add_u32 s8, s12, 0x40080
	v_lshl_add_u64 v[166:167], v[184:185], 0, s[30:31]
	s_addc_u32 s9, s13, 0
	s_add_i32 s12, s73, s33
	global_load_lds_dwordx4 v[166:167], off
	v_lshl_add_u64 v[166:167], s[8:9], 0, v[132:133]
	s_mov_b32 m0, s12
	s_nop 0
	global_load_lds_dwordx4 v[166:167], off
	v_lshl_add_u64 v[166:167], s[8:9], 0, v[128:129]
	s_add_i32 m0, s12, 0x2000
	s_nop 0
	global_load_lds_dwordx4 v[166:167], off
	v_lshl_add_u64 v[166:167], v[232:233], 0, s[30:31]
	s_mov_b32 m0, s54
	s_nop 0
	global_load_lds_dwordx4 v[166:167], off
	v_lshl_add_u64 v[166:167], v[234:235], 0, s[30:31]
	s_mov_b32 m0, s55
	s_nop 0
	global_load_lds_dwordx4 v[166:167], off
	s_waitcnt vmcnt(8) lgkmcnt(0)
	s_barrier
	s_setprio 1
	v_mfma_f32_16x16x32_bf16 v[60:63], v[148:151], v[200:203], v[60:63]
	v_mfma_f32_16x16x32_bf16 v[16:19], v[158:161], v[200:203], v[16:19]
	v_mfma_f32_16x16x32_bf16 v[56:59], v[148:151], v[208:211], v[56:59]
	v_mfma_f32_16x16x32_bf16 v[20:23], v[158:161], v[208:211], v[20:23]
	v_mfma_f32_16x16x32_bf16 v[52:55], v[148:151], v[216:219], v[52:55]
	v_mfma_f32_16x16x32_bf16 v[24:27], v[158:161], v[216:219], v[24:27]
	v_mfma_f32_16x16x32_bf16 v[48:51], v[148:151], v[224:227], v[48:51]
	v_mfma_f32_16x16x32_bf16 v[28:31], v[158:161], v[224:227], v[28:31]
	v_mfma_f32_16x16x32_bf16 v[60:63], v[154:157], v[204:207], v[60:63]
	v_mfma_f32_16x16x32_bf16 v[16:19], v[162:165], v[204:207], v[16:19]
	v_mfma_f32_16x16x32_bf16 v[56:59], v[154:157], v[212:215], v[56:59]
	v_mfma_f32_16x16x32_bf16 v[20:23], v[162:165], v[212:215], v[20:23]
	v_mfma_f32_16x16x32_bf16 v[52:55], v[154:157], v[220:223], v[52:55]
	v_mfma_f32_16x16x32_bf16 v[24:27], v[162:165], v[220:223], v[24:27]
	v_mfma_f32_16x16x32_bf16 v[48:51], v[154:157], v[228:231], v[48:51]
	v_mfma_f32_16x16x32_bf16 v[28:31], v[162:165], v[228:231], v[28:31]
	s_setprio 0
	s_setprio 1
	v_mfma_f32_16x16x32_bf16 v[44:47], v[172:175], v[200:203], v[44:47]
	v_mfma_f32_16x16x32_bf16 v[0:3], v[180:183], v[200:203], v[0:3]
	v_mfma_f32_16x16x32_bf16 v[40:43], v[172:175], v[208:211], v[40:43]
	v_mfma_f32_16x16x32_bf16 v[4:7], v[180:183], v[208:211], v[4:7]
	v_mfma_f32_16x16x32_bf16 v[36:39], v[172:175], v[216:219], v[36:39]
	v_mfma_f32_16x16x32_bf16 v[8:11], v[180:183], v[216:219], v[8:11]
	v_mfma_f32_16x16x32_bf16 v[32:35], v[172:175], v[224:227], v[32:35]
	v_mfma_f32_16x16x32_bf16 v[12:15], v[180:183], v[224:227], v[12:15]
	v_mfma_f32_16x16x32_bf16 v[44:47], v[176:179], v[204:207], v[44:47]
	v_mfma_f32_16x16x32_bf16 v[0:3], v[196:199], v[204:207], v[0:3]
	v_mfma_f32_16x16x32_bf16 v[40:43], v[176:179], v[212:215], v[40:43]
	v_mfma_f32_16x16x32_bf16 v[4:7], v[196:199], v[212:215], v[4:7]
	v_mfma_f32_16x16x32_bf16 v[36:39], v[176:179], v[220:223], v[36:39]
	v_mfma_f32_16x16x32_bf16 v[8:11], v[196:199], v[220:223], v[8:11]
	v_mfma_f32_16x16x32_bf16 v[32:35], v[176:179], v[228:231], v[32:35]
	v_mfma_f32_16x16x32_bf16 v[12:15], v[196:199], v[228:231], v[12:15]
	s_setprio 0
	s_barrier
	s_add_i32 s71, s71, 2
	s_add_u32 s69, s69, 0x100
	s_addc_u32 s70, s70, 0
	s_cmp_gt_u32 s71, 13
	s_mov_b64 s[8:9], s[10:11]
	s_cbranch_scc0 .LBB0_745
	s_and_b64 vcc, exec, s[84:85]
	s_cbranch_vccz .LBB0_748
	s_barrier

; #define PG8_STAGE(bufoff, gbase, voff) do { _Pragma("unroll") for (int _i = 0; _i < 2; ++_i) \
;         __builtin_amdgcn_global_load_lds((const unsigned*)((const char*)(gbase) + (voff)[_i]), (PG8_LAS unsigned*)(lds + (bufoff) + ldsw + _i * 8192), 16, 0, 0); } while (0)
; #define PG8_LDA(dst, b, h) do { _Pragma("unroll") for (int m = 0; m < 4; ++m) _Pragma("unroll") for (int k = 0; k < 2; ++k) dst[m][k] = *(const PG8_LAS bf16x8*)(lds + PG8_SA(b, h) + aoff + m * 2048 + k * 1024); } while (0)
; #define PG8_LDB(dst, b, h) do { _Pragma("unroll") for (int n = 0; n < 2; ++n) _Pragma("unroll") for (int k = 0; k < 2; ++k) dst[n][k] = *(const PG8_LAS bf16x8*)(lds + PG8_SB(b, h) + boff + n * 2048 + k * 1024); } while (0)
; #define PG8_MMA(ai, bj, At, Bt) do { __builtin_amdgcn_s_setprio(1); _Pragma("unroll") for (int m = 0; m < 4; ++m) _Pragma("unroll") for (int n = 0; n < 2; ++n) _Pragma("unroll") for (int k = 0; k < 2; ++k) \
;         acc[ai][bj][m][n] = __builtin_amdgcn_mfma_f32_16x16x32_bf16(Bt[n][k], At[m][k], acc[ai][bj][m][n], 0, 0, 0); __builtin_amdgcn_s_setprio(0); } while (0)
; #define PG8_WAIT_V(n) asm volatile("s_waitcnt vmcnt(" #n ")" ::: "memory")
; #define PG8_BAR __builtin_amdgcn_s_barrier()
; template <class Epi, class Sched, bool ALIGN_EPI = false, bool SP2 = false>
; __device__ __forceinline__ void gemm_phase(PG8_LAS unsigned char* lds, const Gemm g, const Sched& S, const Epi& E) {
;     ...
;         for (int t = 0; t < nt; t += 2) {
;             const bool last = (t == nt - 2);
;             const char* a1 = cA + (size_t)(t + 1) * kstep;
;             const char* a2 = last ? nA : cA + (size_t)(t + 2) * kstep; const char* b2 = last ? nB : cB + (size_t)(t + 2) * kstep;
;             const char* a3 = a2 + kstep; const char* b3 = b2 + kstep;
;             if (last && has_next) S.a_ready(nxt);
;             if constexpr (SP2) {
;             PG8_LDB(B0, 0, 0); PG8_LDB(B1, 0, 1); PG8_SCHED; PG8_LDA(At, 0, 0); PG8_STAGE(PG8_SA(1, 1), a1 + hstep, voffA);
;             PG8_WAIT_V(8); PG8_WAIT_L(0); PG8_BAR; PG8_MMA(0, 0, At, B0); PG8_MMA(0, 1, At, B1); PG8_BAR; PG8_SCHED;
;             PG8_LDA(At, 0, 1); PG8_STAGE(PG8_SB(0, 0), b2, voffB); PG8_STAGE(PG8_SB(0, 1), b2 + hstep, voffB); PG8_STAGE(PG8_SA(0, 0), a2, voffA);
;             PG8_WAIT_V(8); PG8_WAIT_L(0); PG8_BAR; PG8_MMA(1, 0, At, B0); PG8_MMA(1, 1, At, B1); PG8_BAR; PG8_SCHED;
.LBB0_913:
	ds_read_b128 v[128:131], v191
	ds_read_b128 v[132:135], v191 offset:1024
	ds_read_b128 v[136:139], v191 offset:2048
	ds_read_b128 v[140:143], v191 offset:3072
	ds_read_b128 v[144:147], v192
	ds_read_b128 v[148:151], v192 offset:1024
	ds_read_b128 v[170:173], v192 offset:2048
	ds_read_b128 v[174:177], v192 offset:3072
	s_add_u32 s30, s28, 0xfff50080
	s_addc_u32 s31, s29, -1
	s_cmp_eq_u32 s54, 40
	s_cselect_b32 s35, s5, s31
	s_cselect_b32 s34, s4, s30
	s_cselect_b32 s31, s27, s53
	s_cselect_b32 s30, s26, s52
	v_lshl_add_u64 v[186:187], s[28:29], 0, v[162:163]
	s_add_i32 m0, s36, 0xc000
	ds_read_b128 v[178:181], v193
	ds_read_b128 v[182:185], v193 offset:1024
	ds_read_b128 v[196:199], v193 offset:2048
	ds_read_b128 v[200:203], v193 offset:3072
	ds_read_b128 v[204:207], v193 offset:4096
	ds_read_b128 v[208:211], v193 offset:5120
	ds_read_b128 v[212:215], v193 offset:6144
	ds_read_b128 v[216:219], v193 offset:7168
	global_load_lds_dwordx4 v[186:187], off
	v_lshl_add_u64 v[186:187], s[28:29], 0, v[164:165]
	s_add_i32 m0, s36, 0xe000
	s_nop 0
	global_load_lds_dwordx4 v[186:187], off
	s_waitcnt vmcnt(8) lgkmcnt(0)
	s_barrier
	s_setprio 1
	v_mfma_f32_16x16x32_bf16 v[124:127], v[128:131], v[178:181], v[124:127]
	v_mfma_f32_16x16x32_bf16 v[120:123], v[136:139], v[178:181], v[120:123]
	v_mfma_f32_16x16x32_bf16 v[108:111], v[128:131], v[196:199], v[108:111]
	v_mfma_f32_16x16x32_bf16 v[104:107], v[136:139], v[196:199], v[104:107]
	v_mfma_f32_16x16x32_bf16 v[92:95], v[128:131], v[204:207], v[92:95]
	v_mfma_f32_16x16x32_bf16 v[88:91], v[136:139], v[204:207], v[88:91]
	v_mfma_f32_16x16x32_bf16 v[76:79], v[128:131], v[212:215], v[76:79]
	v_mfma_f32_16x16x32_bf16 v[72:75], v[136:139], v[212:215], v[72:75]
	v_mfma_f32_16x16x32_bf16 v[124:127], v[132:135], v[182:185], v[124:127]
	v_mfma_f32_16x16x32_bf16 v[120:123], v[140:143], v[182:185], v[120:123]
	v_mfma_f32_16x16x32_bf16 v[108:111], v[132:135], v[200:203], v[108:111]
	v_mfma_f32_16x16x32_bf16 v[104:107], v[140:143], v[200:203], v[104:107]
	v_mfma_f32_16x16x32_bf16 v[92:95], v[132:135], v[208:211], v[92:95]
	v_mfma_f32_16x16x32_bf16 v[88:91], v[140:143], v[208:211], v[88:91]
	v_mfma_f32_16x16x32_bf16 v[76:79], v[132:135], v[216:219], v[76:79]
	v_mfma_f32_16x16x32_bf16 v[72:75], v[140:143], v[216:219], v[72:75]
	s_setprio 0
	s_setprio 1
	v_mfma_f32_16x16x32_bf16 v[116:119], v[144:147], v[178:181], v[116:119]
	v_mfma_f32_16x16x32_bf16 v[112:115], v[170:173], v[178:181], v[112:115]
	v_mfma_f32_16x16x32_bf16 v[100:103], v[144:147], v[196:199], v[100:103]
	v_mfma_f32_16x16x32_bf16 v[96:99], v[170:173], v[196:199], v[96:99]
	v_mfma_f32_16x16x32_bf16 v[84:87], v[144:147], v[204:207], v[84:87]
	v_mfma_f32_16x16x32_bf16 v[80:83], v[170:173], v[204:207], v[80:83]
	v_mfma_f32_16x16x32_bf16 v[68:71], v[144:147], v[212:215], v[68:71]
	v_mfma_f32_16x16x32_bf16 v[64:67], v[170:173], v[212:215], v[64:67]
	v_mfma_f32_16x16x32_bf16 v[116:119], v[148:151], v[182:185], v[116:119]
	v_mfma_f32_16x16x32_bf16 v[112:115], v[174:177], v[182:185], v[112:115]
	v_mfma_f32_16x16x32_bf16 v[100:103], v[148:151], v[200:203], v[100:103]
	v_mfma_f32_16x16x32_bf16 v[96:99], v[174:177], v[200:203], v[96:99]
	v_mfma_f32_16x16x32_bf16 v[84:87], v[148:151], v[208:211], v[84:87]
	v_mfma_f32_16x16x32_bf16 v[80:83], v[174:177], v[208:211], v[80:83]
	v_mfma_f32_16x16x32_bf16 v[68:71], v[148:151], v[216:219], v[68:71]
	v_mfma_f32_16x16x32_bf16 v[64:67], v[174:177], v[216:219], v[64:67]
	s_setprio 0
	s_barrier
	s_add_i32 s55, s46, s33
	v_lshl_add_u64 v[186:187], s[30:31], 0, v[156:157]
	s_mov_b32 m0, s55
	ds_read_b128 v[178:181], v193 offset:16384
	ds_read_b128 v[182:185], v193 offset:17408
	ds_read_b128 v[196:199], v193 offset:18432
	ds_read_b128 v[200:203], v193 offset:19456
	ds_read_b128 v[204:207], v193 offset:20480
	ds_read_b128 v[208:211], v193 offset:21504
	ds_read_b128 v[212:215], v193 offset:22528
	ds_read_b128 v[216:219], v193 offset:23552
	global_load_lds_dwordx4 v[186:187], off
	s_add_i32 m0, s55, 0x2000
	s_add_u32 s56, s30, 0xb0000
	v_lshl_add_u64 v[220:221], s[30:31], 0, v[160:161]
	s_addc_u32 s57, s31, 0
	s_add_i32 s55, s47, s33
	global_load_lds_dwordx4 v[220:221], off
	v_lshl_add_u64 v[222:223], s[56:57], 0, v[156:157]
	s_mov_b32 m0, s55
	v_lshl_add_u64 v[224:225], s[34:35], 0, v[158:159]
	global_load_lds_dwordx4 v[222:223], off
	v_lshl_add_u64 v[222:223], s[56:57], 0, v[160:161]
	s_add_i32 m0, s55, 0x2000
	s_nop 0
	global_load_lds_dwordx4 v[222:223], off
	v_lshl_add_u64 v[222:223], s[34:35], 0, v[154:155]
	s_mov_b32 m0, s36
	s_nop 0
	global_load_lds_dwordx4 v[222:223], off
	s_mov_b32 m0, s37
	s_nop 0
	global_load_lds_dwordx4 v[224:225], off
	s_waitcnt vmcnt(8) lgkmcnt(0)
	s_barrier
; #define PG8_STAGE(bufoff, gbase, voff) do { _Pragma("unroll") for (int _i = 0; _i < 2; ++_i) \
;         __builtin_amdgcn_global_load_lds((const unsigned*)((const char*)(gbase) + (voff)[_i]), (PG8_LAS unsigned*)(lds + (bufoff) + ldsw + _i * 8192), 16, 0, 0); } while (0)
; #define PG8_LDA(dst, b, h) do { _Pragma("unroll") for (int m = 0; m < 4; ++m) _Pragma("unroll") for (int k = 0; k < 2; ++k) dst[m][k] = *(const PG8_LAS bf16x8*)(lds + PG8_SA(b, h) + aoff + m * 2048 + k * 1024); } while (0)
; #define PG8_LDB(dst, b, h) do { _Pragma("unroll") for (int n = 0; n < 2; ++n) _Pragma("unroll") for (int k = 0; k < 2; ++k) dst[n][k] = *(const PG8_LAS bf16x8*)(lds + PG8_SB(b, h) + boff + n * 2048 + k * 1024); } while (0)
; #define PG8_MMA(ai, bj, At, Bt) do { __builtin_amdgcn_s_setprio(1); _Pragma("unroll") for (int m = 0; m < 4; ++m) _Pragma("unroll") for (int n = 0; n < 2; ++n) _Pragma("unroll") for (int k = 0; k < 2; ++k) \
;         acc[ai][bj][m][n] = __builtin_amdgcn_mfma_f32_16x16x32_bf16(Bt[n][k], At[m][k], acc[ai][bj][m][n], 0, 0, 0); __builtin_amdgcn_s_setprio(0); } while (0)
; #define PG8_WAIT_V(n) asm volatile("s_waitcnt vmcnt(" #n ")" ::: "memory")
; #define PG8_WAIT_L(n) asm volatile("s_waitcnt lgkmcnt(" #n ")" ::: "memory")
; #define PG8_BAR __builtin_amdgcn_s_barrier()
; #define PG8_SCHED __builtin_amdgcn_sched_barrier(0)
; template <class Epi, class Sched, bool ALIGN_EPI = false, bool SP2 = false>
; __device__ __forceinline__ void gemm_phase(PG8_LAS unsigned char* lds, const Gemm g, const Sched& S, const Epi& E) {
;     ...
;             PG8_WAIT_V(8); PG8_WAIT_L(0); PG8_BAR; PG8_MMA(1, 0, At, B0); PG8_MMA(1, 1, At, B1); PG8_BAR; PG8_SCHED;
;             PG8_LDB(B0, 1, 0); PG8_LDB(B1, 1, 1); PG8_SCHED; PG8_LDA(At, 1, 0); PG8_STAGE(PG8_SA(0, 1), a2 + hstep, voffA);
;             PG8_WAIT_V(8); PG8_WAIT_L(0); PG8_BAR; PG8_MMA(0, 0, At, B0); PG8_MMA(0, 1, At, B1); PG8_BAR; PG8_SCHED;
	s_setprio 1
	v_mfma_f32_16x16x32_bf16 v[60:63], v[128:131], v[178:181], v[60:63]
	v_mfma_f32_16x16x32_bf16 v[56:59], v[136:139], v[178:181], v[56:59]
	v_mfma_f32_16x16x32_bf16 v[44:47], v[128:131], v[196:199], v[44:47]
	v_mfma_f32_16x16x32_bf16 v[40:43], v[136:139], v[196:199], v[40:43]
	v_mfma_f32_16x16x32_bf16 v[28:31], v[128:131], v[204:207], v[28:31]
	v_mfma_f32_16x16x32_bf16 v[24:27], v[136:139], v[204:207], v[24:27]
	v_mfma_f32_16x16x32_bf16 v[12:15], v[128:131], v[212:215], v[12:15]
	v_mfma_f32_16x16x32_bf16 v[8:11], v[136:139], v[212:215], v[8:11]
	v_mfma_f32_16x16x32_bf16 v[60:63], v[132:135], v[182:185], v[60:63]
	v_mfma_f32_16x16x32_bf16 v[56:59], v[140:143], v[182:185], v[56:59]
	v_mfma_f32_16x16x32_bf16 v[44:47], v[132:135], v[200:203], v[44:47]
	v_mfma_f32_16x16x32_bf16 v[40:43], v[140:143], v[200:203], v[40:43]
	v_mfma_f32_16x16x32_bf16 v[28:31], v[132:135], v[208:211], v[28:31]
	v_mfma_f32_16x16x32_bf16 v[24:27], v[140:143], v[208:211], v[24:27]
	v_mfma_f32_16x16x32_bf16 v[12:15], v[132:135], v[216:219], v[12:15]
	v_mfma_f32_16x16x32_bf16 v[8:11], v[140:143], v[216:219], v[8:11]
	s_setprio 0
	s_setprio 1
	v_mfma_f32_16x16x32_bf16 v[52:55], v[144:147], v[178:181], v[52:55]
	v_mfma_f32_16x16x32_bf16 v[48:51], v[170:173], v[178:181], v[48:51]
	v_mfma_f32_16x16x32_bf16 v[36:39], v[144:147], v[196:199], v[36:39]
	v_mfma_f32_16x16x32_bf16 v[32:35], v[170:173], v[196:199], v[32:35]
	v_mfma_f32_16x16x32_bf16 v[20:23], v[144:147], v[204:207], v[20:23]
	v_mfma_f32_16x16x32_bf16 v[16:19], v[170:173], v[204:207], v[16:19]
	v_mfma_f32_16x16x32_bf16 v[4:7], v[144:147], v[212:215], v[4:7]
	v_mfma_f32_16x16x32_bf16 v[0:3], v[170:173], v[212:215], v[0:3]
	v_mfma_f32_16x16x32_bf16 v[52:55], v[148:151], v[182:185], v[52:55]
	v_mfma_f32_16x16x32_bf16 v[48:51], v[174:177], v[182:185], v[48:51]
	v_mfma_f32_16x16x32_bf16 v[36:39], v[148:151], v[200:203], v[36:39]
	v_mfma_f32_16x16x32_bf16 v[32:35], v[174:177], v[200:203], v[32:35]
	v_mfma_f32_16x16x32_bf16 v[20:23], v[148:151], v[208:211], v[20:23]
	v_mfma_f32_16x16x32_bf16 v[16:19], v[174:177], v[208:211], v[16:19]
	v_mfma_f32_16x16x32_bf16 v[4:7], v[148:151], v[216:219], v[4:7]
	v_mfma_f32_16x16x32_bf16 v[0:3], v[174:177], v[216:219], v[0:3]
	s_setprio 0
	s_barrier
	s_add_i32 s55, 0, 0x18000
	s_add_i32 s56, 0, 0x1c000
	v_add_u32_e32 v140, s55, v189
	v_add_u32_e32 v174, s56, v189
	ds_read_b128 v[128:131], v140
	ds_read_b128 v[132:135], v140 offset:1024
	ds_read_b128 v[136:139], v140 offset:2048
	ds_read_b128 v[140:143], v140 offset:3072
	ds_read_b128 v[144:147], v174
	ds_read_b128 v[148:151], v174 offset:1024
	ds_read_b128 v[170:173], v174 offset:2048
	ds_read_b128 v[174:177], v174 offset:3072
	s_add_u32 s34, s34, 0xb0000
	s_addc_u32 s35, s35, 0
	s_mov_b32 m0, s38
	v_lshl_add_u64 v[226:227], s[34:35], 0, v[154:155]
	ds_read_b128 v[178:181], v193 offset:32768
	ds_read_b128 v[182:185], v193 offset:33792
	ds_read_b128 v[196:199], v193 offset:34816
	ds_read_b128 v[200:203], v193 offset:35840
	ds_read_b128 v[204:207], v193 offset:36864
	ds_read_b128 v[208:211], v193 offset:37888
	ds_read_b128 v[212:215], v193 offset:38912
	ds_read_b128 v[216:219], v193 offset:39936
	global_load_lds_dwordx4 v[226:227], off
	v_lshl_add_u64 v[226:227], s[34:35], 0, v[158:159]
	s_mov_b32 m0, s39
	s_nop 0
	global_load_lds_dwordx4 v[226:227], off
	s_waitcnt vmcnt(8) lgkmcnt(0)
	s_barrier
	s_setprio 1
	v_mfma_f32_16x16x32_bf16 v[124:127], v[128:131], v[178:181], v[124:127]
	v_mfma_f32_16x16x32_bf16 v[120:123], v[136:139], v[178:181], v[120:123]
	v_mfma_f32_16x16x32_bf16 v[108:111], v[128:131], v[196:199], v[108:111]
	v_mfma_f32_16x16x32_bf16 v[104:107], v[136:139], v[196:199], v[104:107]
	v_mfma_f32_16x16x32_bf16 v[92:95], v[128:131], v[204:207], v[92:95]
	v_mfma_f32_16x16x32_bf16 v[88:91], v[136:139], v[204:207], v[88:91]
	v_mfma_f32_16x16x32_bf16 v[76:79], v[128:131], v[212:215], v[76:79]
	v_mfma_f32_16x16x32_bf16 v[72:75], v[136:139], v[212:215], v[72:75]
	v_mfma_f32_16x16x32_bf16 v[124:127], v[132:135], v[182:185], v[124:127]
	v_mfma_f32_16x16x32_bf16 v[120:123], v[140:143], v[182:185], v[120:123]
	v_mfma_f32_16x16x32_bf16 v[108:111], v[132:135], v[200:203], v[108:111]
	v_mfma_f32_16x16x32_bf16 v[104:107], v[140:143], v[200:203], v[104:107]
	v_mfma_f32_16x16x32_bf16 v[92:95], v[132:135], v[208:211], v[92:95]
	v_mfma_f32_16x16x32_bf16 v[88:91], v[140:143], v[208:211], v[88:91]
	v_mfma_f32_16x16x32_bf16 v[76:79], v[132:135], v[216:219], v[76:79]
	v_mfma_f32_16x16x32_bf16 v[72:75], v[140:143], v[216:219], v[72:75]
	s_setprio 0
	s_setprio 1
	v_mfma_f32_16x16x32_bf16 v[116:119], v[144:147], v[178:181], v[116:119]
	v_mfma_f32_16x16x32_bf16 v[112:115], v[170:173], v[178:181], v[112:115]
	v_mfma_f32_16x16x32_bf16 v[100:103], v[144:147], v[196:199], v[100:103]
	v_mfma_f32_16x16x32_bf16 v[96:99], v[170:173], v[196:199], v[96:99]
	v_mfma_f32_16x16x32_bf16 v[84:87], v[144:147], v[204:207], v[84:87]
	v_mfma_f32_16x16x32_bf16 v[80:83], v[170:173], v[204:207], v[80:83]
	v_mfma_f32_16x16x32_bf16 v[68:71], v[144:147], v[212:215], v[68:71]
	v_mfma_f32_16x16x32_bf16 v[64:67], v[170:173], v[212:215], v[64:67]
	v_mfma_f32_16x16x32_bf16 v[116:119], v[148:151], v[182:185], v[116:119]
	v_mfma_f32_16x16x32_bf16 v[112:115], v[174:177], v[182:185], v[112:115]
	v_mfma_f32_16x16x32_bf16 v[100:103], v[148:151], v[200:203], v[100:103]
	v_mfma_f32_16x16x32_bf16 v[96:99], v[174:177], v[200:203], v[96:99]
	v_mfma_f32_16x16x32_bf16 v[84:87], v[148:151], v[208:211], v[84:87]
	v_mfma_f32_16x16x32_bf16 v[80:83], v[174:177], v[208:211], v[80:83]
	v_mfma_f32_16x16x32_bf16 v[68:71], v[148:151], v[216:219], v[68:71]
	v_mfma_f32_16x16x32_bf16 v[64:67], v[174:177], v[216:219], v[64:67]
	s_setprio 0
	s_barrier
; #define PG8_STAGE(bufoff, gbase, voff) do { _Pragma("unroll") for (int _i = 0; _i < 2; ++_i) \
;         __builtin_amdgcn_global_load_lds((const unsigned*)((const char*)(gbase) + (voff)[_i]), (PG8_LAS unsigned*)(lds + (bufoff) + ldsw + _i * 8192), 16, 0, 0); } while (0)
; #define PG8_LDA(dst, b, h) do { _Pragma("unroll") for (int m = 0; m < 4; ++m) _Pragma("unroll") for (int k = 0; k < 2; ++k) dst[m][k] = *(const PG8_LAS bf16x8*)(lds + PG8_SA(b, h) + aoff + m * 2048 + k * 1024); } while (0)
; #define PG8_MMA(ai, bj, At, Bt) do { __builtin_amdgcn_s_setprio(1); _Pragma("unroll") for (int m = 0; m < 4; ++m) _Pragma("unroll") for (int n = 0; n < 2; ++n) _Pragma("unroll") for (int k = 0; k < 2; ++k) \
;         acc[ai][bj][m][n] = __builtin_amdgcn_mfma_f32_16x16x32_bf16(Bt[n][k], At[m][k], acc[ai][bj][m][n], 0, 0, 0); __builtin_amdgcn_s_setprio(0); } while (0)
; #define PG8_WAIT_V(n) asm volatile("s_waitcnt vmcnt(" #n ")" ::: "memory")
; #define PG8_WAIT_L(n) asm volatile("s_waitcnt lgkmcnt(" #n ")" ::: "memory")
; #define PG8_BAR __builtin_amdgcn_s_barrier()
; #define PG8_SCHED __builtin_amdgcn_sched_barrier(0)
; template <class Epi, class Sched, bool ALIGN_EPI = false, bool SP2 = false>
; __device__ __forceinline__ void gemm_phase(PG8_LAS unsigned char* lds, const Gemm g, const Sched& S, const Epi& E) {
;     ...
;             PG8_LDA(At, 1, 1); PG8_STAGE(PG8_SB(1, 0), b3, voffB); PG8_STAGE(PG8_SB(1, 1), b3 + hstep, voffB); PG8_STAGE(PG8_SA(1, 0), a3, voffA);
;             PG8_WAIT_V(8); PG8_WAIT_L(0); PG8_BAR; PG8_MMA(1, 0, At, B0); PG8_MMA(1, 1, At, B1); PG8_BAR; PG8_SCHED;
;     ...
;         if constexpr (ALIGN_EPI) { if (wr == 0) PG8_BAR; }
	s_add_i32 s34, s55, s33
	v_lshl_add_u64 v[186:187], v[186:187], 0, s[18:19]
	s_mov_b32 m0, s34
	ds_read_b128 v[178:181], v193 offset:49152
	ds_read_b128 v[182:185], v193 offset:50176
	ds_read_b128 v[196:199], v193 offset:51200
	ds_read_b128 v[200:203], v193 offset:52224
	ds_read_b128 v[204:207], v193 offset:53248
	ds_read_b128 v[208:211], v193 offset:54272
	ds_read_b128 v[212:215], v193 offset:55296
	ds_read_b128 v[216:219], v193 offset:56320
	global_load_lds_dwordx4 v[186:187], off
	s_add_i32 m0, s34, 0x2000
	s_add_u32 s30, s30, 0xb0080
	v_lshl_add_u64 v[186:187], v[220:221], 0, s[18:19]
	s_addc_u32 s31, s31, 0
	s_add_i32 s34, s56, s33
	global_load_lds_dwordx4 v[186:187], off
	v_lshl_add_u64 v[186:187], s[30:31], 0, v[156:157]
	s_mov_b32 m0, s34
	s_nop 0
	global_load_lds_dwordx4 v[186:187], off
	v_lshl_add_u64 v[186:187], s[30:31], 0, v[160:161]
	s_add_i32 m0, s34, 0x2000
	s_nop 0
	global_load_lds_dwordx4 v[186:187], off
	v_lshl_add_u64 v[186:187], v[222:223], 0, s[18:19]
	s_mov_b32 m0, s41
	s_nop 0
	global_load_lds_dwordx4 v[186:187], off
	v_lshl_add_u64 v[186:187], v[224:225], 0, s[18:19]
	s_mov_b32 m0, s42
	s_nop 0
	global_load_lds_dwordx4 v[186:187], off
	s_waitcnt vmcnt(8) lgkmcnt(0)
	s_barrier
	s_setprio 1
	v_mfma_f32_16x16x32_bf16 v[60:63], v[128:131], v[178:181], v[60:63]
	v_mfma_f32_16x16x32_bf16 v[56:59], v[136:139], v[178:181], v[56:59]
	v_mfma_f32_16x16x32_bf16 v[44:47], v[128:131], v[196:199], v[44:47]
	v_mfma_f32_16x16x32_bf16 v[40:43], v[136:139], v[196:199], v[40:43]
	v_mfma_f32_16x16x32_bf16 v[28:31], v[128:131], v[204:207], v[28:31]
	v_mfma_f32_16x16x32_bf16 v[24:27], v[136:139], v[204:207], v[24:27]
	v_mfma_f32_16x16x32_bf16 v[12:15], v[128:131], v[212:215], v[12:15]
	v_mfma_f32_16x16x32_bf16 v[8:11], v[136:139], v[212:215], v[8:11]
	v_mfma_f32_16x16x32_bf16 v[60:63], v[132:135], v[182:185], v[60:63]
	v_mfma_f32_16x16x32_bf16 v[56:59], v[140:143], v[182:185], v[56:59]
	v_mfma_f32_16x16x32_bf16 v[44:47], v[132:135], v[200:203], v[44:47]
	v_mfma_f32_16x16x32_bf16 v[40:43], v[140:143], v[200:203], v[40:43]
	v_mfma_f32_16x16x32_bf16 v[28:31], v[132:135], v[208:211], v[28:31]
	v_mfma_f32_16x16x32_bf16 v[24:27], v[140:143], v[208:211], v[24:27]
	v_mfma_f32_16x16x32_bf16 v[12:15], v[132:135], v[216:219], v[12:15]
	v_mfma_f32_16x16x32_bf16 v[8:11], v[140:143], v[216:219], v[8:11]
	s_setprio 0
	s_setprio 1
	v_mfma_f32_16x16x32_bf16 v[52:55], v[144:147], v[178:181], v[52:55]
	v_mfma_f32_16x16x32_bf16 v[48:51], v[170:173], v[178:181], v[48:51]
	v_mfma_f32_16x16x32_bf16 v[36:39], v[144:147], v[196:199], v[36:39]
	v_mfma_f32_16x16x32_bf16 v[32:35], v[170:173], v[196:199], v[32:35]
	v_mfma_f32_16x16x32_bf16 v[20:23], v[144:147], v[204:207], v[20:23]
	v_mfma_f32_16x16x32_bf16 v[16:19], v[170:173], v[204:207], v[16:19]
	v_mfma_f32_16x16x32_bf16 v[4:7], v[144:147], v[212:215], v[4:7]
	v_mfma_f32_16x16x32_bf16 v[0:3], v[170:173], v[212:215], v[0:3]
	v_mfma_f32_16x16x32_bf16 v[52:55], v[148:151], v[182:185], v[52:55]
	v_mfma_f32_16x16x32_bf16 v[48:51], v[174:177], v[182:185], v[48:51]
	v_mfma_f32_16x16x32_bf16 v[36:39], v[148:151], v[200:203], v[36:39]
	v_mfma_f32_16x16x32_bf16 v[32:35], v[174:177], v[200:203], v[32:35]
	v_mfma_f32_16x16x32_bf16 v[20:23], v[148:151], v[208:211], v[20:23]
	v_mfma_f32_16x16x32_bf16 v[16:19], v[174:177], v[208:211], v[16:19]
	v_mfma_f32_16x16x32_bf16 v[4:7], v[148:151], v[216:219], v[4:7]
	v_mfma_f32_16x16x32_bf16 v[0:3], v[174:177], v[216:219], v[0:3]
	s_setprio 0
	s_barrier
	s_add_i32 s54, s54, 2
	s_add_u32 s28, s28, 0x100
	s_addc_u32 s29, s29, 0
	s_add_u32 s52, s52, 0x100
	s_addc_u32 s53, s53, 0
	s_cmp_gt_u32 s54, 41
	s_cbranch_scc0 .LBB0_913
	s_and_b64 vcc, exec, s[24:25]
	s_cbranch_vccz .LBB0_916
	s_barrier
